# all grid barriers XCD-local (census-checked, global fallback), transients re-based into owning XCD rows, attention/final_norm remapped to XCD-owned rows, no setprio
# speedup vs baseline: 1.0166x; 1.0029x over previous
.LBB0_144:
	s_add_u32 s30, s8, 0xa900000
	s_addc_u32 s31, s9, 0
	s_add_u32 s34, s8, 0x12d00000
	s_addc_u32 s35, s9, 0
	s_and_b32 s98, s2, 7
	s_mul_i32 s98, s98, 0xe00000
	s_add_u32 s34, s34, s98
	s_addc_u32 s35, s35, 0
	s_add_i32 m0, s59, 0x18000
	v_lshl_add_u64 v[8:9], v[8:9], 0, s[14:15]
	s_waitcnt vmcnt(2)
	s_barrier
	global_load_lds_dwordx4 v[8:9], off
	v_lshl_add_u64 v[4:5], v[4:5], 0, s[14:15]
	s_add_i32 m0, s59, 0x1a000
	s_add_i32 s63, s59, 0x8000
	global_load_lds_dwordx4 v[4:5], off
	v_lshl_add_u64 v[4:5], v[6:7], 0, s[14:15]
	s_mov_b32 m0, s63
	s_add_i32 s66, s59, 0xa000
	global_load_lds_dwordx4 v[4:5], off
	v_lshl_add_u64 v[4:5], v[10:11], 0, s[14:15]
	s_mov_b32 m0, s66
	v_lshl_add_u64 v[2:3], v[2:3], 0, s[14:15]
	global_load_lds_dwordx4 v[4:5], off
	s_add_i32 m0, s59, 0x1c000
	v_lshl_add_u64 v[0:1], v[0:1], 0, s[14:15]
	global_load_lds_dwordx4 v[2:3], off
	s_add_i32 m0, s59, 0x1e000
	v_and_b32_e32 v222, 15, v12
	global_load_lds_dwordx4 v[0:1], off
	v_bfe_u32 v0, v12, 4, 2
	s_lshr_b32 s1, s1, 26
	s_add_i32 s1, s0, s1
	v_lshlrev_b32_e32 v2, 4, v0
	v_lshlrev_b32_e32 v3, 2, v222
	s_and_b32 s4, s12, 3
	s_ashr_i32 s67, s1, 6
	v_lshl_or_b32 v2, v222, 6, v2
	s_lshl_b32 s1, s11, 13
	v_and_b32_e32 v4, 32, v3
	s_lshl_b32 s68, s11, 6
	v_bitop3_b32 v5, v2, s1, v4 bitop3:0xde
	s_lshl_b32 s1, s4, 12
	s_cmp_gt_i32 s0, 63
	s_cselect_b64 s[36:37], -1, 0
	s_add_i32 s69, s67, -2
	s_cmpk_lt_u32 s10, 0x100
	s_cselect_b64 s[94:95], -1, 0
	s_lshl_b32 s0, s11, 11
	v_lshlrev_b32_e32 v1, 3, v0
	v_bitop3_b32 v223, v2, s1, v4 bitop3:0xde
	s_lshl_b32 s1, s4, 9
	v_cmp_eq_u32_e64 s[38:39], 0, v0
	s_add_i32 s0, s0, 0
	v_add_u32_e32 v0, v18, v16
	s_waitcnt vmcnt(6)
	s_add_i32 s0, s0, s1
	v_add_lshl_u32 v176, v0, v17, 1
	v_add_u32_e32 v0, v15, v13
	v_lshl_or_b32 v224, s4, 5, v1
	s_add_i32 s0, s0, 0x20400
	v_lshl_add_u64 v[194:195], s[24:25], 0, v[176:177]
	v_add_lshl_u32 v176, v0, v14, 1
	v_or_b32_e32 v225, 0xfffff800, v224
	v_and_b32_e32 v226, 63, v12
	s_mov_b32 s70, 0
	v_add_u32_e32 v227, s0, v3
	v_lshl_add_u64 v[196:197], s[24:25], 0, v[176:177]
	s_mov_b32 s96, -1
	v_add_u32_e32 v228, 0, v5
	v_readlane_b32 s75, v253, 52
	v_readlane_b32 s46, v253, 54
	s_barrier
	s_branch .LBB0_147

.LBB0_165:
	v_lshl_add_u32 v202, s75, 8, v225
	v_lshlrev_b32_e32 v231, 1, v202
	v_lshlrev_b32_e32 v199, 11, v198
	v_mov_b32_e32 v203, v177
	v_add_u32_e32 v176, v199, v231
	v_and_b32_e32 v205, 0xce, v198
	v_lshlrev_b64 v[136:137], 2, v[202:203]
	v_add_u32_e32 v152, 0xfffff800, v176
	v_cmp_eq_u32_e64 s[44:45], 0, v205
	v_add_u32_e32 v153, 0xfffff000, v176
	v_or_b32_e32 v203, 0x8000, v199
	v_lshl_add_u64 v[200:201], s[22:23], 0, v[136:137]
	v_lshl_add_u64 v[138:139], s[20:21], 0, v[136:137]
	v_lshl_add_u64 v[148:149], s[18:19], 0, v[136:137]
	v_cndmask_b32_e64 v152, v152, v176, s[44:45]
	v_cndmask_b32_e64 v153, v153, v176, s[44:45]
	v_add_u32_e32 v206, v203, v231
	s_waitcnt lgkmcnt(0)
	global_load_dwordx4 v[128:131], v[200:201], off offset:16
	global_load_dwordx4 v[140:143], v[200:201], off
	global_load_dwordx4 v[132:135], v[138:139], off offset:16
	global_load_dwordx4 v[144:147], v[138:139], off
	s_nop 0
	global_load_dwordx4 v[136:139], v[148:149], off offset:16
	s_nop 0
	global_load_dwordx4 v[148:151], v[148:149], off
	s_nop 0
	global_load_dwordx4 v[168:171], v152, s[30:31]
	global_load_dwordx4 v[164:167], v153, s[30:31]
	v_add_u32_e32 v152, 0xfffff800, v206
	v_add_u32_e32 v153, 0xfffff000, v206
	global_load_dwordx4 v[172:175], v176, s[30:31]
	global_load_dwordx4 v[160:163], v206, s[30:31]
	global_load_dwordx4 v[156:159], v152, s[30:31]
	s_nop 0
	global_load_dwordx4 v[152:155], v153, s[30:31]
	ds_read_b32 v204, v227
	v_cmp_ne_u32_e32 vcc, 0, v205
	v_mov_b64_e32 v[216:217], 0xe900000
	s_waitcnt lgkmcnt(0)
	v_pk_mul_f32 v[212:213], v[122:123], v[204:205] op_sel_hi:[1,0]
	v_pk_mul_f32 v[214:215], v[120:121], v[204:205] op_sel_hi:[1,0]
	v_pk_mul_f32 v[208:209], v[118:119], v[204:205] op_sel_hi:[1,0]
	v_pk_mul_f32 v[210:211], v[116:117], v[204:205] op_sel_hi:[1,0]
	v_mov_b64_e32 v[204:205], 0xe900000
	s_and_saveexec_b64 s[42:43], vcc
	s_cbranch_execz .LBB0_167
	s_waitcnt vmcnt(0)
	v_lshlrev_b32_e32 v238, 16, v164
	v_and_b32_e32 v239, 0xffff0000, v164
	v_lshlrev_b32_e32 v164, 16, v165
	v_and_b32_e32 v165, 0xffff0000, v165
	v_lshlrev_b32_e32 v234, 16, v168
	v_and_b32_e32 v235, 0xffff0000, v168
	v_lshlrev_b32_e32 v168, 16, v169
	v_and_b32_e32 v169, 0xffff0000, v169
	v_pk_mul_f32 v[164:165], v[142:143], v[164:165]
	v_lshlrev_b32_e32 v216, 16, v172
	v_and_b32_e32 v217, 0xffff0000, v172
	v_lshlrev_b32_e32 v172, 16, v173
	v_and_b32_e32 v173, 0xffff0000, v173
	v_pk_fma_f32 v[164:165], v[146:147], v[168:169], v[164:165]
	v_lshlrev_b32_e32 v240, 16, v166
	v_and_b32_e32 v241, 0xffff0000, v166
	v_lshlrev_b32_e32 v166, 16, v167
	v_and_b32_e32 v167, 0xffff0000, v167
	v_pk_fma_f32 v[164:165], v[150:151], v[172:173], v[164:165]
	v_lshlrev_b32_e32 v236, 16, v170
	v_and_b32_e32 v237, 0xffff0000, v170
	v_lshlrev_b32_e32 v170, 16, v171
	v_and_b32_e32 v171, 0xffff0000, v171
	v_pk_mul_f32 v[238:239], v[140:141], v[238:239]
	v_pk_mul_f32 v[212:213], v[212:213], v[164:165]
	v_pk_mul_f32 v[164:165], v[128:129], v[240:241]
	v_pk_mul_f32 v[166:167], v[130:131], v[166:167]
	v_lshlrev_b32_e32 v232, 16, v174
	v_and_b32_e32 v233, 0xffff0000, v174
	v_lshlrev_b32_e32 v174, 16, v175
	v_and_b32_e32 v175, 0xffff0000, v175
	v_pk_fma_f32 v[168:169], v[144:145], v[234:235], v[238:239]
	v_pk_fma_f32 v[166:167], v[134:135], v[170:171], v[166:167]
	v_pk_fma_f32 v[164:165], v[132:133], v[236:237], v[164:165]
	v_pk_fma_f32 v[168:169], v[148:149], v[216:217], v[168:169]
	v_pk_fma_f32 v[164:165], v[136:137], v[232:233], v[164:165]
	v_pk_fma_f32 v[166:167], v[138:139], v[174:175], v[166:167]
	v_pk_mul_f32 v[214:215], v[214:215], v[168:169]
	v_pk_mul_f32 v[208:209], v[208:209], v[166:167]
	v_pk_mul_f32 v[210:211], v[210:211], v[164:165]
	v_mov_b64_e32 v[216:217], 0x12d00000
	s_and_b32 s98, s2, 7
	s_mul_i32 s98, s98, 0xe00000
	v_add_u32_e32 v216, s98, v216
.LBB0_167:
	s_or_b64 exec, exec, s[42:43]
	s_waitcnt vmcnt(0)
	ds_read_b32 v170, v227 offset:64
	v_cvt_pk_bf16_f32 v165, v212, v213
	v_lshlrev_b32_e32 v212, 16, v152
	v_and_b32_e32 v213, 0xffff0000, v152
	v_lshlrev_b32_e32 v152, 16, v153
	v_and_b32_e32 v153, 0xffff0000, v153
	v_lshl_add_u64 v[168:169], s[8:9], 0, v[216:217]
	v_cvt_pk_bf16_f32 v167, v208, v209
	v_lshlrev_b32_e32 v208, 16, v156
	v_and_b32_e32 v209, 0xffff0000, v156
	v_lshlrev_b32_e32 v156, 16, v157
	v_and_b32_e32 v157, 0xffff0000, v157
	v_pk_mul_f32 v[212:213], v[140:141], v[212:213]
	v_pk_mul_f32 v[152:153], v[142:143], v[152:153]
	v_cvt_pk_bf16_f32 v164, v214, v215
	v_cvt_pk_bf16_f32 v166, v210, v211
	v_lshl_add_u64 v[168:169], v[168:169], 0, v[176:177]
	v_lshlrev_b32_e32 v172, 16, v160
	v_and_b32_e32 v173, 0xffff0000, v160
	v_lshlrev_b32_e32 v160, 16, v161
	v_and_b32_e32 v161, 0xffff0000, v161
	v_pk_fma_f32 v[152:153], v[146:147], v[156:157], v[152:153]
	v_pk_fma_f32 v[156:157], v[144:145], v[208:209], v[212:213]
	global_store_dwordx4 v[168:169], v[164:167], off
	s_waitcnt lgkmcnt(0)
	v_pk_mul_f32 v[168:169], v[110:111], v[170:171] op_sel_hi:[1,0]
	v_lshlrev_b32_e32 v214, 16, v154
	v_pk_mul_f32 v[164:165], v[102:103], v[170:171] op_sel_hi:[1,0]
	v_pk_mul_f32 v[166:167], v[100:101], v[170:171] op_sel_hi:[1,0]
	v_pk_mul_f32 v[170:171], v[108:109], v[170:171] op_sel_hi:[1,0]
	v_and_b32_e32 v215, 0xffff0000, v154
	v_lshlrev_b32_e32 v154, 16, v155
	v_and_b32_e32 v155, 0xffff0000, v155
	v_pk_fma_f32 v[156:157], v[148:149], v[172:173], v[156:157]
	v_pk_fma_f32 v[152:153], v[150:151], v[160:161], v[152:153]
	v_lshlrev_b32_e32 v210, 16, v158
	v_and_b32_e32 v211, 0xffff0000, v158
	v_lshlrev_b32_e32 v158, 16, v159
	v_and_b32_e32 v159, 0xffff0000, v159
	v_pk_mul_f32 v[160:161], v[152:153], v[168:169]
	v_pk_mul_f32 v[152:153], v[156:157], v[170:171]
	v_pk_mul_f32 v[156:157], v[128:129], v[214:215]
	v_pk_mul_f32 v[154:155], v[130:131], v[154:155]
	v_lshlrev_b32_e32 v174, 16, v162
	v_and_b32_e32 v175, 0xffff0000, v162
	v_lshlrev_b32_e32 v162, 16, v163
	v_and_b32_e32 v163, 0xffff0000, v163
	v_pk_fma_f32 v[154:155], v[134:135], v[158:159], v[154:155]
	v_pk_fma_f32 v[156:157], v[132:133], v[210:211], v[156:157]
	v_pk_fma_f32 v[154:155], v[138:139], v[162:163], v[154:155]
	v_pk_fma_f32 v[156:157], v[136:137], v[174:175], v[156:157]
	v_mov_b32_e32 v207, v177
	v_pk_mul_f32 v[158:159], v[154:155], v[164:165]
	v_pk_mul_f32 v[154:155], v[156:157], v[166:167]
	v_or_b32_e32 v216, 0x10000, v199
	v_cvt_pk_bf16_f32 v152, v152, v153
	v_cvt_pk_bf16_f32 v153, v160, v161
	v_cvt_pk_bf16_f32 v154, v154, v155
	v_cvt_pk_bf16_f32 v155, v158, v159
	v_lshl_add_u64 v[156:157], s[34:35], 0, v[206:207]
	v_add_u32_e32 v176, v216, v231
	global_store_dwordx4 v[156:157], v[152:155], off
	v_add_u32_e32 v156, 0xfffff800, v176
	v_add_u32_e32 v160, 0xfffff000, v176
	global_load_dwordx4 v[156:159], v156, s[30:31]
	v_or_b32_e32 v217, 0x18000, v199
	global_load_dwordx4 v[160:163], v160, s[30:31]
	v_add_u32_e32 v229, v217, v231
	global_load_dwordx4 v[152:155], v176, s[30:31]
	global_load_dwordx4 v[164:167], v229, s[30:31]
	v_add_u32_e32 v168, 0xfffff800, v229
	v_add_u32_e32 v172, 0xfffff000, v229
	global_load_dwordx4 v[168:171], v168, s[30:31]
	v_add_u32_e32 v230, 0x48000, v199
	global_load_dwordx4 v[172:175], v172, s[30:31]
	ds_read2_b32 v[206:207], v227 offset0:32 offset1:48
	s_waitcnt lgkmcnt(0)
	v_pk_mul_f32 v[212:213], v[94:95], v[206:207] op_sel_hi:[1,0]
	v_pk_mul_f32 v[214:215], v[92:93], v[206:207] op_sel_hi:[1,0]
	v_pk_mul_f32 v[208:209], v[86:87], v[206:207] op_sel_hi:[1,0]
	v_pk_mul_f32 v[210:211], v[84:85], v[206:207] op_sel_hi:[1,0]
	s_waitcnt vmcnt(5)
	v_lshlrev_b32_e32 v236, 16, v156
	v_and_b32_e32 v237, 0xffff0000, v156
	s_waitcnt vmcnt(4)
	v_lshlrev_b32_e32 v240, 16, v160
	v_and_b32_e32 v241, 0xffff0000, v160
	v_lshlrev_b32_e32 v160, 16, v161
	v_and_b32_e32 v161, 0xffff0000, v161
	v_lshlrev_b32_e32 v156, 16, v157
	v_and_b32_e32 v157, 0xffff0000, v157
	v_pk_mul_f32 v[240:241], v[140:141], v[240:241]
	v_pk_mul_f32 v[160:161], v[142:143], v[160:161]
	s_waitcnt vmcnt(3)
	v_lshlrev_b32_e32 v232, 16, v152
	v_and_b32_e32 v233, 0xffff0000, v152
	v_lshlrev_b32_e32 v152, 16, v153
	v_and_b32_e32 v153, 0xffff0000, v153
	v_pk_fma_f32 v[156:157], v[146:147], v[156:157], v[160:161]
	v_pk_fma_f32 v[160:161], v[144:145], v[236:237], v[240:241]
	v_lshlrev_b32_e32 v242, 16, v162
	v_and_b32_e32 v243, 0xffff0000, v162
	v_lshlrev_b32_e32 v162, 16, v163
	v_and_b32_e32 v163, 0xffff0000, v163
	v_pk_fma_f32 v[160:161], v[148:149], v[232:233], v[160:161]
	v_pk_fma_f32 v[152:153], v[150:151], v[152:153], v[156:157]
	v_lshlrev_b32_e32 v238, 16, v158
	v_and_b32_e32 v239, 0xffff0000, v158
	v_lshlrev_b32_e32 v158, 16, v159
	v_and_b32_e32 v159, 0xffff0000, v159
	v_pk_mul_f32 v[156:157], v[212:213], v[152:153]
	v_pk_mul_f32 v[152:153], v[214:215], v[160:161]
	v_pk_mul_f32 v[160:161], v[128:129], v[242:243]
	v_pk_mul_f32 v[162:163], v[130:131], v[162:163]
	v_lshlrev_b32_e32 v234, 16, v154
	v_and_b32_e32 v235, 0xffff0000, v154
	v_lshlrev_b32_e32 v154, 16, v155
	v_and_b32_e32 v155, 0xffff0000, v155
	v_pk_fma_f32 v[158:159], v[134:135], v[158:159], v[162:163]
	v_pk_fma_f32 v[160:161], v[132:133], v[238:239], v[160:161]
	v_pk_fma_f32 v[154:155], v[138:139], v[154:155], v[158:159]
	v_pk_fma_f32 v[160:161], v[136:137], v[234:235], v[160:161]
	v_pk_mul_f32 v[158:159], v[208:209], v[154:155]
	v_pk_mul_f32 v[154:155], v[210:211], v[160:161]
	v_cvt_pk_bf16_f32 v152, v152, v153
	v_cvt_pk_bf16_f32 v153, v156, v157
	v_cvt_pk_bf16_f32 v154, v154, v155
	v_cvt_pk_bf16_f32 v155, v158, v159
	s_waitcnt vmcnt(0)
	v_lshlrev_b32_e32 v210, 16, v172
	v_and_b32_e32 v211, 0xffff0000, v172
	v_lshlrev_b32_e32 v172, 16, v173
	v_and_b32_e32 v173, 0xffff0000, v173
	global_store_dwordx4 v176, v[152:155], s[34:35]
	v_lshlrev_b32_e32 v206, 16, v168
	v_pk_mul_f32 v[210:211], v[140:141], v[210:211]
	v_mov_b32_e32 v152, v207
	v_and_b32_e32 v207, 0xffff0000, v168
	v_lshlrev_b32_e32 v168, 16, v169
	v_and_b32_e32 v169, 0xffff0000, v169
	v_pk_mul_f32 v[172:173], v[142:143], v[172:173]
	v_lshlrev_b32_e32 v160, 16, v164
	v_and_b32_e32 v161, 0xffff0000, v164
	v_lshlrev_b32_e32 v162, 16, v165
	v_and_b32_e32 v163, 0xffff0000, v165
	v_pk_fma_f32 v[168:169], v[146:147], v[168:169], v[172:173]
	v_pk_fma_f32 v[172:173], v[144:145], v[206:207], v[210:211]
	v_pk_mul_f32 v[154:155], v[70:71], v[152:153] op_sel_hi:[1,0]
	v_pk_mul_f32 v[156:157], v[68:69], v[152:153] op_sel_hi:[1,0]
	v_pk_mul_f32 v[158:159], v[78:79], v[152:153] op_sel_hi:[1,0]
	v_pk_mul_f32 v[152:153], v[76:77], v[152:153] op_sel_hi:[1,0]
	v_lshlrev_b32_e32 v212, 16, v174
	v_and_b32_e32 v213, 0xffff0000, v174
	v_lshlrev_b32_e32 v174, 16, v175
	v_and_b32_e32 v175, 0xffff0000, v175
	v_pk_fma_f32 v[160:161], v[148:149], v[160:161], v[172:173]
	v_pk_fma_f32 v[162:163], v[150:151], v[162:163], v[168:169]
	v_lshlrev_b32_e32 v208, 16, v170
	v_and_b32_e32 v209, 0xffff0000, v170
	v_lshlrev_b32_e32 v170, 16, v171
	v_and_b32_e32 v171, 0xffff0000, v171
	v_pk_mul_f32 v[158:159], v[158:159], v[162:163]
	v_pk_mul_f32 v[152:153], v[152:153], v[160:161]
	v_pk_mul_f32 v[160:161], v[128:129], v[212:213]
	v_pk_mul_f32 v[162:163], v[130:131], v[174:175]
	v_lshlrev_b32_e32 v164, 16, v166
	v_and_b32_e32 v165, 0xffff0000, v166
	v_lshlrev_b32_e32 v166, 16, v167
	v_and_b32_e32 v167, 0xffff0000, v167
	v_pk_fma_f32 v[162:163], v[134:135], v[170:171], v[162:163]
	v_pk_fma_f32 v[160:161], v[132:133], v[208:209], v[160:161]
	v_pk_fma_f32 v[162:163], v[138:139], v[166:167], v[162:163]
	v_pk_fma_f32 v[160:161], v[136:137], v[164:165], v[160:161]
	v_pk_mul_f32 v[162:163], v[154:155], v[162:163]
	v_pk_mul_f32 v[154:155], v[156:157], v[160:161]
	v_cvt_pk_bf16_f32 v152, v152, v153
	v_cvt_pk_bf16_f32 v153, v158, v159
	v_cvt_pk_bf16_f32 v154, v154, v155
	v_cvt_pk_bf16_f32 v155, v162, v163
	global_store_dwordx4 v229, v[152:155], s[34:35]
	v_add_u32_e32 v206, v230, v231
	s_nop 0
	v_add_u32_e32 v152, 0x80, v198
	v_lshlrev_b32_e32 v229, 11, v152
	v_add_u32_e32 v176, v229, v231
	v_and_b32_e32 v207, 0xce, v152
	v_add_u32_e32 v152, 0xfffff800, v176
	v_cmp_eq_u32_e64 s[46:47], 0, v207
	v_add_u32_e32 v153, 0xfffff000, v176
	v_cmp_ne_u32_e64 s[42:43], 0, v207
	v_cndmask_b32_e64 v152, v152, v176, s[46:47]
	v_cndmask_b32_e64 v153, v153, v176, s[46:47]
	global_load_dwordx4 v[168:171], v152, s[30:31]
	global_load_dwordx4 v[164:167], v153, s[30:31]
	v_add_u32_e32 v152, 0xfffff800, v206
	v_add_u32_e32 v153, 0xfffff000, v206
	global_load_dwordx4 v[172:175], v176, s[30:31]
	global_load_dwordx4 v[160:163], v206, s[30:31]
	global_load_dwordx4 v[156:159], v152, s[30:31]
	s_nop 0
	global_load_dwordx4 v[152:155], v153, s[30:31]
	ds_read_b32 v210, v227 offset:256
	s_waitcnt lgkmcnt(0)
	v_pk_mul_f32 v[212:213], v[62:63], v[210:211] op_sel_hi:[1,0]
	v_pk_mul_f32 v[214:215], v[60:61], v[210:211] op_sel_hi:[1,0]
	v_pk_mul_f32 v[208:209], v[54:55], v[210:211] op_sel_hi:[1,0]
	v_pk_mul_f32 v[210:211], v[52:53], v[210:211] op_sel_hi:[1,0]
	s_and_saveexec_b64 s[10:11], s[42:43]
	s_cbranch_execz .LBB0_169
	s_waitcnt vmcnt(4)
	v_lshlrev_b32_e32 v238, 16, v164
	v_and_b32_e32 v239, 0xffff0000, v164
	v_lshlrev_b32_e32 v164, 16, v165
	v_and_b32_e32 v165, 0xffff0000, v165
	v_lshlrev_b32_e32 v234, 16, v168
	v_and_b32_e32 v235, 0xffff0000, v168
	v_lshlrev_b32_e32 v168, 16, v169
	v_and_b32_e32 v169, 0xffff0000, v169
	v_pk_mul_f32 v[164:165], v[142:143], v[164:165]
	s_waitcnt vmcnt(3)
	v_lshlrev_b32_e32 v204, 16, v172
	v_and_b32_e32 v205, 0xffff0000, v172
	v_lshlrev_b32_e32 v172, 16, v173
	v_and_b32_e32 v173, 0xffff0000, v173
	v_pk_fma_f32 v[164:165], v[146:147], v[168:169], v[164:165]
	v_lshlrev_b32_e32 v240, 16, v166
	v_and_b32_e32 v241, 0xffff0000, v166
	v_lshlrev_b32_e32 v166, 16, v167
	v_and_b32_e32 v167, 0xffff0000, v167
	v_pk_fma_f32 v[164:165], v[150:151], v[172:173], v[164:165]
	v_lshlrev_b32_e32 v236, 16, v170
	v_and_b32_e32 v237, 0xffff0000, v170
	v_lshlrev_b32_e32 v170, 16, v171
	v_and_b32_e32 v171, 0xffff0000, v171
	v_pk_mul_f32 v[238:239], v[140:141], v[238:239]
	v_pk_mul_f32 v[212:213], v[212:213], v[164:165]
	v_pk_mul_f32 v[164:165], v[128:129], v[240:241]
	v_pk_mul_f32 v[166:167], v[130:131], v[166:167]
	v_lshlrev_b32_e32 v232, 16, v174
	v_and_b32_e32 v233, 0xffff0000, v174
	v_lshlrev_b32_e32 v174, 16, v175
	v_and_b32_e32 v175, 0xffff0000, v175
	v_pk_fma_f32 v[168:169], v[144:145], v[234:235], v[238:239]
	v_pk_fma_f32 v[166:167], v[134:135], v[170:171], v[166:167]
	v_pk_fma_f32 v[164:165], v[132:133], v[236:237], v[164:165]
	v_pk_fma_f32 v[168:169], v[148:149], v[204:205], v[168:169]
	v_pk_fma_f32 v[164:165], v[136:137], v[232:233], v[164:165]
	v_pk_fma_f32 v[166:167], v[138:139], v[174:175], v[166:167]
	v_pk_mul_f32 v[214:215], v[214:215], v[168:169]
	v_pk_mul_f32 v[208:209], v[208:209], v[166:167]
	v_pk_mul_f32 v[210:211], v[210:211], v[164:165]
	v_mov_b64_e32 v[204:205], 0x12d00000
	s_and_b32 s98, s2, 7
	s_mul_i32 s98, s98, 0xe00000
	v_add_u32_e32 v204, s98, v204
.LBB0_169:
	s_or_b64 exec, exec, s[10:11]
	s_waitcnt vmcnt(5)
	ds_read_b32 v170, v227 offset:320
	s_waitcnt vmcnt(4)
	v_cvt_pk_bf16_f32 v166, v210, v211
	s_waitcnt vmcnt(0)
	v_lshlrev_b32_e32 v210, 16, v152
	v_and_b32_e32 v211, 0xffff0000, v152
	v_lshlrev_b32_e32 v152, 16, v153
	v_and_b32_e32 v153, 0xffff0000, v153
	v_lshl_add_u64 v[168:169], s[8:9], 0, v[204:205]
	v_lshlrev_b32_e32 v204, 16, v156
	v_and_b32_e32 v205, 0xffff0000, v156
	v_lshlrev_b32_e32 v156, 16, v157
	v_and_b32_e32 v157, 0xffff0000, v157
	v_pk_mul_f32 v[210:211], v[140:141], v[210:211]
	v_pk_mul_f32 v[152:153], v[142:143], v[152:153]
	v_cvt_pk_bf16_f32 v164, v214, v215
	v_cvt_pk_bf16_f32 v165, v212, v213
	v_cvt_pk_bf16_f32 v167, v208, v209
	v_lshl_add_u64 v[168:169], v[168:169], 0, v[176:177]
	v_lshlrev_b32_e32 v172, 16, v160
	v_and_b32_e32 v173, 0xffff0000, v160
	v_lshlrev_b32_e32 v160, 16, v161
	v_and_b32_e32 v161, 0xffff0000, v161
	v_pk_fma_f32 v[152:153], v[146:147], v[156:157], v[152:153]
	v_pk_fma_f32 v[156:157], v[144:145], v[204:205], v[210:211]
	global_store_dwordx4 v[168:169], v[164:167], off
	v_lshlrev_b32_e32 v212, 16, v154
	v_and_b32_e32 v213, 0xffff0000, v154
	s_waitcnt lgkmcnt(0)
	v_pk_mul_f32 v[164:165], v[46:47], v[170:171] op_sel_hi:[1,0]
	v_pk_mul_f32 v[166:167], v[44:45], v[170:171] op_sel_hi:[1,0]
	v_lshlrev_b32_e32 v154, 16, v155
	v_and_b32_e32 v155, 0xffff0000, v155
	v_pk_fma_f32 v[156:157], v[148:149], v[172:173], v[156:157]
	v_pk_fma_f32 v[152:153], v[150:151], v[160:161], v[152:153]
	v_lshlrev_b32_e32 v208, 16, v158
	v_and_b32_e32 v209, 0xffff0000, v158
	v_lshlrev_b32_e32 v158, 16, v159
	v_and_b32_e32 v159, 0xffff0000, v159
	v_pk_mul_f32 v[160:161], v[152:153], v[164:165]
	v_pk_mul_f32 v[152:153], v[156:157], v[166:167]
	v_pk_mul_f32 v[156:157], v[128:129], v[212:213]
	v_pk_mul_f32 v[154:155], v[130:131], v[154:155]
	v_lshlrev_b32_e32 v174, 16, v162
	v_and_b32_e32 v175, 0xffff0000, v162
	v_lshlrev_b32_e32 v162, 16, v163
	v_and_b32_e32 v163, 0xffff0000, v163
	v_pk_fma_f32 v[154:155], v[134:135], v[158:159], v[154:155]
	v_pk_fma_f32 v[156:157], v[132:133], v[208:209], v[156:157]
	v_pk_mul_f32 v[168:169], v[38:39], v[170:171] op_sel_hi:[1,0]
	v_pk_mul_f32 v[170:171], v[36:37], v[170:171] op_sel_hi:[1,0]
	v_pk_fma_f32 v[156:157], v[136:137], v[174:175], v[156:157]
	v_pk_fma_f32 v[154:155], v[138:139], v[162:163], v[154:155]
	v_mov_b32_e32 v207, v177
	v_pk_mul_f32 v[158:159], v[154:155], v[168:169]
	v_pk_mul_f32 v[154:155], v[156:157], v[170:171]
	v_add_u32_e32 v214, 0x50000, v199
	v_cvt_pk_bf16_f32 v152, v152, v153
	v_cvt_pk_bf16_f32 v153, v160, v161
	v_cvt_pk_bf16_f32 v154, v154, v155
	v_cvt_pk_bf16_f32 v155, v158, v159
	v_lshl_add_u64 v[156:157], s[34:35], 0, v[206:207]
	v_add_u32_e32 v176, v214, v231
	global_store_dwordx4 v[156:157], v[152:155], off
	v_add_u32_e32 v156, 0xfffff800, v176
	v_add_u32_e32 v160, 0xfffff000, v176
	global_load_dwordx4 v[156:159], v156, s[30:31]
	v_add_u32_e32 v215, 0x58000, v199
	global_load_dwordx4 v[160:163], v160, s[30:31]
	v_add_u32_e32 v231, v215, v231
	global_load_dwordx4 v[152:155], v176, s[30:31]
	global_load_dwordx4 v[164:167], v231, s[30:31]
	v_add_u32_e32 v168, 0xfffff800, v231
	v_add_u32_e32 v172, 0xfffff000, v231
	global_load_dwordx4 v[168:171], v168, s[30:31]
	s_waitcnt vmcnt(4)
	v_lshlrev_b32_e32 v236, 16, v156
	global_load_dwordx4 v[172:175], v172, s[30:31]
	ds_read2_b32 v[204:205], v227 offset0:96 offset1:112
	s_waitcnt vmcnt(4)
	v_lshlrev_b32_e32 v240, 16, v160
	v_and_b32_e32 v241, 0xffff0000, v160
	v_lshlrev_b32_e32 v160, 16, v161
	v_and_b32_e32 v161, 0xffff0000, v161
	v_and_b32_e32 v237, 0xffff0000, v156
	v_lshlrev_b32_e32 v156, 16, v157
	v_and_b32_e32 v157, 0xffff0000, v157
	v_pk_mul_f32 v[240:241], v[140:141], v[240:241]
	v_pk_mul_f32 v[160:161], v[142:143], v[160:161]
	s_waitcnt vmcnt(3)
	v_lshlrev_b32_e32 v232, 16, v152
	v_and_b32_e32 v233, 0xffff0000, v152
	v_lshlrev_b32_e32 v152, 16, v153
	v_and_b32_e32 v153, 0xffff0000, v153
	v_pk_fma_f32 v[156:157], v[146:147], v[156:157], v[160:161]
	v_pk_fma_f32 v[160:161], v[144:145], v[236:237], v[240:241]
	s_waitcnt lgkmcnt(0)
	v_pk_mul_f32 v[206:207], v[30:31], v[204:205] op_sel_hi:[1,0]
	v_pk_mul_f32 v[208:209], v[28:29], v[204:205] op_sel_hi:[1,0]
	v_lshlrev_b32_e32 v242, 16, v162
	v_and_b32_e32 v243, 0xffff0000, v162
	v_lshlrev_b32_e32 v162, 16, v163
	v_and_b32_e32 v163, 0xffff0000, v163
	v_pk_fma_f32 v[160:161], v[148:149], v[232:233], v[160:161]
	v_pk_fma_f32 v[152:153], v[150:151], v[152:153], v[156:157]
	v_lshlrev_b32_e32 v238, 16, v158
	v_and_b32_e32 v239, 0xffff0000, v158
	v_lshlrev_b32_e32 v158, 16, v159
	v_and_b32_e32 v159, 0xffff0000, v159
	v_pk_mul_f32 v[156:157], v[206:207], v[152:153]
	v_pk_mul_f32 v[152:153], v[208:209], v[160:161]
	v_pk_mul_f32 v[160:161], v[128:129], v[242:243]
	v_pk_mul_f32 v[162:163], v[130:131], v[162:163]
	v_lshlrev_b32_e32 v234, 16, v154
	v_and_b32_e32 v235, 0xffff0000, v154
	v_lshlrev_b32_e32 v154, 16, v155
	v_and_b32_e32 v155, 0xffff0000, v155
	v_pk_fma_f32 v[158:159], v[134:135], v[158:159], v[162:163]
	v_pk_fma_f32 v[160:161], v[132:133], v[238:239], v[160:161]
	v_pk_mul_f32 v[210:211], v[22:23], v[204:205] op_sel_hi:[1,0]
	v_pk_mul_f32 v[212:213], v[20:21], v[204:205] op_sel_hi:[1,0]
	v_pk_fma_f32 v[160:161], v[136:137], v[234:235], v[160:161]
	v_pk_fma_f32 v[154:155], v[138:139], v[154:155], v[158:159]
	v_cvt_pk_bf16_f32 v152, v152, v153
	v_pk_mul_f32 v[158:159], v[210:211], v[154:155]
	v_pk_mul_f32 v[154:155], v[212:213], v[160:161]
	v_cvt_pk_bf16_f32 v153, v156, v157
	v_cvt_pk_bf16_f32 v154, v154, v155
	v_cvt_pk_bf16_f32 v155, v158, v159
	global_store_dwordx4 v176, v[152:155], s[34:35]
	s_waitcnt vmcnt(2)
	v_lshlrev_b32_e32 v204, 16, v168
	v_lshlrev_b32_e32 v206, 16, v170
	v_mov_b32_e32 v152, v205
	v_and_b32_e32 v205, 0xffff0000, v168
	v_lshlrev_b32_e32 v168, 16, v169
	v_and_b32_e32 v169, 0xffff0000, v169
	v_and_b32_e32 v207, 0xffff0000, v170
	v_lshlrev_b32_e32 v170, 16, v171
	v_and_b32_e32 v171, 0xffff0000, v171
	v_lshlrev_b32_e32 v160, 16, v164
	v_and_b32_e32 v161, 0xffff0000, v164
	v_lshlrev_b32_e32 v162, 16, v165
	v_and_b32_e32 v163, 0xffff0000, v165
	v_lshlrev_b32_e32 v164, 16, v166
	v_and_b32_e32 v165, 0xffff0000, v166
	v_lshlrev_b32_e32 v166, 16, v167
	v_and_b32_e32 v167, 0xffff0000, v167
	v_pk_mul_f32 v[154:155], v[14:15], v[152:153] op_sel_hi:[1,0]
	v_pk_mul_f32 v[156:157], v[12:13], v[152:153] op_sel_hi:[1,0]
	v_pk_mul_f32 v[158:159], v[6:7], v[152:153] op_sel_hi:[1,0]
	v_pk_mul_f32 v[152:153], v[4:5], v[152:153] op_sel_hi:[1,0]
	v_or_b32_e32 v176, 0x80, v202
	v_mov_b64_e32 v[212:213], 0xe900000
	s_waitcnt vmcnt(1)
	v_lshlrev_b32_e32 v208, 16, v172
	v_and_b32_e32 v209, 0xffff0000, v172
	v_lshlrev_b32_e32 v172, 16, v173
	v_and_b32_e32 v173, 0xffff0000, v173
	v_lshlrev_b32_e32 v210, 16, v174
	v_and_b32_e32 v211, 0xffff0000, v174
	v_lshlrev_b32_e32 v174, 16, v175
	v_and_b32_e32 v175, 0xffff0000, v175
	v_pk_mul_f32 v[140:141], v[140:141], v[208:209]
	v_pk_mul_f32 v[142:143], v[142:143], v[172:173]
	v_pk_mul_f32 v[128:129], v[128:129], v[210:211]
	v_pk_mul_f32 v[130:131], v[130:131], v[174:175]
	v_pk_fma_f32 v[142:143], v[146:147], v[168:169], v[142:143]
	v_pk_fma_f32 v[140:141], v[144:145], v[204:205], v[140:141]
	v_pk_fma_f32 v[130:131], v[134:135], v[170:171], v[130:131]
	v_pk_fma_f32 v[128:129], v[132:133], v[206:207], v[128:129]
	v_pk_fma_f32 v[140:141], v[148:149], v[160:161], v[140:141]
	v_pk_fma_f32 v[142:143], v[150:151], v[162:163], v[142:143]
	v_pk_fma_f32 v[128:129], v[136:137], v[164:165], v[128:129]
	v_pk_fma_f32 v[130:131], v[138:139], v[166:167], v[130:131]
	v_pk_mul_f32 v[142:143], v[154:155], v[142:143]
	v_pk_mul_f32 v[140:141], v[156:157], v[140:141]
	v_pk_mul_f32 v[132:133], v[158:159], v[130:131]
	v_pk_mul_f32 v[130:131], v[152:153], v[128:129]
	v_cvt_pk_bf16_f32 v128, v140, v141
	v_cvt_pk_bf16_f32 v129, v142, v143
	v_cvt_pk_bf16_f32 v130, v130, v131
	v_cvt_pk_bf16_f32 v131, v132, v133
	global_store_dwordx4 v231, v[128:131], s[34:35]
	v_lshlrev_b32_e32 v231, 1, v176
	v_lshlrev_b64 v[136:137], 2, v[176:177]
	v_add_u32_e32 v176, v199, v231
	v_add_u32_e32 v152, 0xfffff800, v176
	v_add_u32_e32 v153, 0xfffff000, v176
	v_lshl_add_u64 v[138:139], s[20:21], 0, v[136:137]
	v_lshl_add_u64 v[148:149], s[18:19], 0, v[136:137]
	v_cndmask_b32_e64 v152, v152, v176, s[44:45]
	v_cndmask_b32_e64 v153, v153, v176, s[44:45]
	v_add_u32_e32 v202, v203, v231
	global_load_dwordx4 v[128:131], v[200:201], off offset:528
	global_load_dwordx4 v[140:143], v[200:201], off offset:512
	global_load_dwordx4 v[132:135], v[138:139], off offset:16
	global_load_dwordx4 v[144:147], v[138:139], off
	s_nop 0
	global_load_dwordx4 v[136:139], v[148:149], off offset:16
	s_nop 0
	global_load_dwordx4 v[148:151], v[148:149], off
	s_nop 0
	global_load_dwordx4 v[168:171], v152, s[30:31]
	global_load_dwordx4 v[164:167], v153, s[30:31]
	v_add_u32_e32 v152, 0xfffff800, v202
	v_add_u32_e32 v153, 0xfffff000, v202
	global_load_dwordx4 v[172:175], v176, s[30:31]
	global_load_dwordx4 v[160:163], v202, s[30:31]
	global_load_dwordx4 v[156:159], v152, s[30:31]
	s_nop 0
	global_load_dwordx4 v[152:155], v153, s[30:31]
	ds_read_b32 v200, v227
	s_waitcnt lgkmcnt(0)
	v_pk_mul_f32 v[208:209], v[126:127], v[200:201] op_sel_hi:[1,0]
	v_pk_mul_f32 v[210:211], v[124:125], v[200:201] op_sel_hi:[1,0]
	v_pk_mul_f32 v[204:205], v[114:115], v[200:201] op_sel_hi:[1,0]
	v_pk_mul_f32 v[206:207], v[112:113], v[200:201] op_sel_hi:[1,0]
	v_mov_b64_e32 v[200:201], 0xe900000
	s_and_saveexec_b64 s[44:45], vcc
	s_cbranch_execz .LBB0_171
	s_waitcnt vmcnt(4)
	v_lshlrev_b32_e32 v238, 16, v164
	v_and_b32_e32 v239, 0xffff0000, v164
	v_lshlrev_b32_e32 v164, 16, v165
	v_and_b32_e32 v165, 0xffff0000, v165
	v_lshlrev_b32_e32 v234, 16, v168
	v_and_b32_e32 v235, 0xffff0000, v168
	v_lshlrev_b32_e32 v168, 16, v169
	v_and_b32_e32 v169, 0xffff0000, v169
	v_pk_mul_f32 v[164:165], v[142:143], v[164:165]
	s_waitcnt vmcnt(3)
	v_lshlrev_b32_e32 v212, 16, v172
	v_and_b32_e32 v213, 0xffff0000, v172
	v_lshlrev_b32_e32 v172, 16, v173
	v_and_b32_e32 v173, 0xffff0000, v173
	v_pk_fma_f32 v[164:165], v[146:147], v[168:169], v[164:165]
	v_lshlrev_b32_e32 v240, 16, v166
	v_and_b32_e32 v241, 0xffff0000, v166
	v_lshlrev_b32_e32 v166, 16, v167
	v_and_b32_e32 v167, 0xffff0000, v167
	v_pk_fma_f32 v[164:165], v[150:151], v[172:173], v[164:165]
	v_lshlrev_b32_e32 v236, 16, v170
	v_and_b32_e32 v237, 0xffff0000, v170
	v_lshlrev_b32_e32 v170, 16, v171
	v_and_b32_e32 v171, 0xffff0000, v171
	v_pk_mul_f32 v[238:239], v[140:141], v[238:239]
	v_pk_mul_f32 v[208:209], v[208:209], v[164:165]
	v_pk_mul_f32 v[164:165], v[128:129], v[240:241]
	v_pk_mul_f32 v[166:167], v[130:131], v[166:167]
	v_lshlrev_b32_e32 v232, 16, v174
	v_and_b32_e32 v233, 0xffff0000, v174
	v_lshlrev_b32_e32 v174, 16, v175
	v_and_b32_e32 v175, 0xffff0000, v175
	v_pk_fma_f32 v[168:169], v[144:145], v[234:235], v[238:239]
	v_pk_fma_f32 v[166:167], v[134:135], v[170:171], v[166:167]
	v_pk_fma_f32 v[164:165], v[132:133], v[236:237], v[164:165]
	v_pk_fma_f32 v[168:169], v[148:149], v[212:213], v[168:169]
	v_pk_fma_f32 v[164:165], v[136:137], v[232:233], v[164:165]
	v_pk_fma_f32 v[166:167], v[138:139], v[174:175], v[166:167]
	v_pk_mul_f32 v[210:211], v[210:211], v[168:169]
	v_pk_mul_f32 v[204:205], v[204:205], v[166:167]
	v_pk_mul_f32 v[206:207], v[206:207], v[164:165]
	v_mov_b64_e32 v[212:213], 0x12d00000
	s_and_b32 s98, s2, 7
	s_mul_i32 s98, s98, 0xe00000
	v_add_u32_e32 v212, s98, v212
.LBB0_171:
	s_or_b64 exec, exec, s[44:45]
	s_waitcnt vmcnt(5)
	ds_read_b32 v170, v227 offset:64
	s_waitcnt vmcnt(4)
	v_cvt_pk_bf16_f32 v165, v208, v209
	s_waitcnt vmcnt(0)
	v_lshlrev_b32_e32 v208, 16, v152
	v_and_b32_e32 v209, 0xffff0000, v152
	v_lshlrev_b32_e32 v152, 16, v153
	v_and_b32_e32 v153, 0xffff0000, v153
	v_lshl_add_u64 v[168:169], s[8:9], 0, v[212:213]
	v_cvt_pk_bf16_f32 v167, v204, v205
	v_lshlrev_b32_e32 v204, 16, v156
	v_and_b32_e32 v205, 0xffff0000, v156
	v_lshlrev_b32_e32 v156, 16, v157
	v_and_b32_e32 v157, 0xffff0000, v157
	v_pk_mul_f32 v[208:209], v[140:141], v[208:209]
	v_pk_mul_f32 v[152:153], v[142:143], v[152:153]
	v_cvt_pk_bf16_f32 v164, v210, v211
	v_cvt_pk_bf16_f32 v166, v206, v207
	v_lshl_add_u64 v[168:169], v[168:169], 0, v[176:177]
	v_lshlrev_b32_e32 v172, 16, v160
	v_and_b32_e32 v173, 0xffff0000, v160
	v_lshlrev_b32_e32 v160, 16, v161
	v_and_b32_e32 v161, 0xffff0000, v161
	v_pk_fma_f32 v[152:153], v[146:147], v[156:157], v[152:153]
	v_pk_fma_f32 v[156:157], v[144:145], v[204:205], v[208:209]
	global_store_dwordx4 v[168:169], v[164:167], off
	s_waitcnt lgkmcnt(0)
	v_pk_mul_f32 v[168:169], v[106:107], v[170:171] op_sel_hi:[1,0]
	v_lshlrev_b32_e32 v210, 16, v154
	v_pk_mul_f32 v[164:165], v[98:99], v[170:171] op_sel_hi:[1,0]
	v_pk_mul_f32 v[166:167], v[96:97], v[170:171] op_sel_hi:[1,0]
	v_pk_mul_f32 v[170:171], v[104:105], v[170:171] op_sel_hi:[1,0]
	v_and_b32_e32 v211, 0xffff0000, v154
	v_lshlrev_b32_e32 v154, 16, v155
	v_and_b32_e32 v155, 0xffff0000, v155
	v_pk_fma_f32 v[156:157], v[148:149], v[172:173], v[156:157]
	v_pk_fma_f32 v[152:153], v[150:151], v[160:161], v[152:153]
	v_lshlrev_b32_e32 v206, 16, v158
	v_and_b32_e32 v207, 0xffff0000, v158
	v_lshlrev_b32_e32 v158, 16, v159
	v_and_b32_e32 v159, 0xffff0000, v159
	v_pk_mul_f32 v[160:161], v[152:153], v[168:169]
	v_pk_mul_f32 v[152:153], v[156:157], v[170:171]
	v_pk_mul_f32 v[156:157], v[128:129], v[210:211]
	v_pk_mul_f32 v[154:155], v[130:131], v[154:155]
	v_lshlrev_b32_e32 v174, 16, v162
	v_and_b32_e32 v175, 0xffff0000, v162
	v_lshlrev_b32_e32 v162, 16, v163
	v_and_b32_e32 v163, 0xffff0000, v163
	v_pk_fma_f32 v[154:155], v[134:135], v[158:159], v[154:155]
	v_pk_fma_f32 v[156:157], v[132:133], v[206:207], v[156:157]
	v_pk_fma_f32 v[154:155], v[138:139], v[162:163], v[154:155]
	v_pk_fma_f32 v[156:157], v[136:137], v[174:175], v[156:157]
	v_mov_b32_e32 v203, v177
	v_pk_mul_f32 v[158:159], v[154:155], v[164:165]
	v_pk_mul_f32 v[154:155], v[156:157], v[166:167]
	v_cvt_pk_bf16_f32 v152, v152, v153
	v_cvt_pk_bf16_f32 v153, v160, v161
	v_cvt_pk_bf16_f32 v154, v154, v155
	v_cvt_pk_bf16_f32 v155, v158, v159
	v_lshl_add_u64 v[156:157], s[34:35], 0, v[202:203]
	v_add_u32_e32 v176, v216, v231
	global_store_dwordx4 v[156:157], v[152:155], off
	v_add_u32_e32 v156, 0xfffff800, v176
	v_add_u32_e32 v160, 0xfffff000, v176
	global_load_dwordx4 v[156:159], v156, s[30:31]
	v_add_u32_e32 v199, v217, v231
	global_load_dwordx4 v[160:163], v160, s[30:31]
	v_add_u32_e32 v168, 0xfffff800, v199
	global_load_dwordx4 v[152:155], v176, s[30:31]
	global_load_dwordx4 v[164:167], v199, s[30:31]
	v_add_u32_e32 v172, 0xfffff000, v199
	global_load_dwordx4 v[168:171], v168, s[30:31]
	s_waitcnt vmcnt(4)
	v_lshlrev_b32_e32 v232, 16, v156
	global_load_dwordx4 v[172:175], v172, s[30:31]
	ds_read2_b32 v[202:203], v227 offset0:32 offset1:48
	s_waitcnt vmcnt(4)
	v_lshlrev_b32_e32 v236, 16, v160
	v_and_b32_e32 v237, 0xffff0000, v160
	v_lshlrev_b32_e32 v160, 16, v161
	v_and_b32_e32 v161, 0xffff0000, v161
	v_and_b32_e32 v233, 0xffff0000, v156
	v_lshlrev_b32_e32 v156, 16, v157
	v_and_b32_e32 v157, 0xffff0000, v157
	v_pk_mul_f32 v[236:237], v[140:141], v[236:237]
	v_pk_mul_f32 v[160:161], v[142:143], v[160:161]
	s_waitcnt vmcnt(3)
	v_lshlrev_b32_e32 v212, 16, v152
	v_and_b32_e32 v213, 0xffff0000, v152
	v_lshlrev_b32_e32 v152, 16, v153
	v_and_b32_e32 v153, 0xffff0000, v153
	v_pk_fma_f32 v[156:157], v[146:147], v[156:157], v[160:161]
	v_pk_fma_f32 v[160:161], v[144:145], v[232:233], v[236:237]
	s_waitcnt lgkmcnt(0)
	v_pk_mul_f32 v[208:209], v[90:91], v[202:203] op_sel_hi:[1,0]
	v_pk_mul_f32 v[210:211], v[88:89], v[202:203] op_sel_hi:[1,0]
	v_lshlrev_b32_e32 v238, 16, v162
	v_and_b32_e32 v239, 0xffff0000, v162
	v_lshlrev_b32_e32 v162, 16, v163
	v_and_b32_e32 v163, 0xffff0000, v163
	v_pk_fma_f32 v[160:161], v[148:149], v[212:213], v[160:161]
	v_pk_fma_f32 v[152:153], v[150:151], v[152:153], v[156:157]
	v_lshlrev_b32_e32 v234, 16, v158
	v_and_b32_e32 v235, 0xffff0000, v158
	v_lshlrev_b32_e32 v158, 16, v159
	v_and_b32_e32 v159, 0xffff0000, v159
	v_pk_mul_f32 v[156:157], v[208:209], v[152:153]
	v_pk_mul_f32 v[152:153], v[210:211], v[160:161]
	v_pk_mul_f32 v[160:161], v[128:129], v[238:239]
	v_pk_mul_f32 v[162:163], v[130:131], v[162:163]
	v_lshlrev_b32_e32 v216, 16, v154
	v_and_b32_e32 v217, 0xffff0000, v154
	v_lshlrev_b32_e32 v154, 16, v155
	v_and_b32_e32 v155, 0xffff0000, v155
	v_pk_fma_f32 v[158:159], v[134:135], v[158:159], v[162:163]
	v_pk_fma_f32 v[160:161], v[132:133], v[234:235], v[160:161]
	v_pk_mul_f32 v[204:205], v[82:83], v[202:203] op_sel_hi:[1,0]
	v_pk_mul_f32 v[206:207], v[80:81], v[202:203] op_sel_hi:[1,0]
	v_pk_fma_f32 v[160:161], v[136:137], v[216:217], v[160:161]
	v_pk_fma_f32 v[154:155], v[138:139], v[154:155], v[158:159]
	v_cvt_pk_bf16_f32 v152, v152, v153
	v_pk_mul_f32 v[158:159], v[204:205], v[154:155]
	v_pk_mul_f32 v[154:155], v[206:207], v[160:161]
	v_cvt_pk_bf16_f32 v153, v156, v157
	v_cvt_pk_bf16_f32 v154, v154, v155
	v_cvt_pk_bf16_f32 v155, v158, v159
	global_store_dwordx4 v176, v[152:155], s[34:35]
	s_waitcnt vmcnt(2)
	v_lshlrev_b32_e32 v202, 16, v168
	v_lshlrev_b32_e32 v160, 16, v164
	v_mov_b32_e32 v152, v203
	v_and_b32_e32 v203, 0xffff0000, v168
	v_lshlrev_b32_e32 v168, 16, v169
	v_and_b32_e32 v169, 0xffff0000, v169
	v_and_b32_e32 v161, 0xffff0000, v164
	v_lshlrev_b32_e32 v162, 16, v165
	v_and_b32_e32 v163, 0xffff0000, v165
	v_pk_mul_f32 v[154:155], v[66:67], v[152:153] op_sel_hi:[1,0]
	v_pk_mul_f32 v[156:157], v[64:65], v[152:153] op_sel_hi:[1,0]
	v_pk_mul_f32 v[158:159], v[74:75], v[152:153] op_sel_hi:[1,0]
	v_pk_mul_f32 v[152:153], v[72:73], v[152:153] op_sel_hi:[1,0]
	v_lshlrev_b32_e32 v204, 16, v170
	v_and_b32_e32 v205, 0xffff0000, v170
	v_lshlrev_b32_e32 v170, 16, v171
	v_and_b32_e32 v171, 0xffff0000, v171
	v_lshlrev_b32_e32 v164, 16, v166
	v_and_b32_e32 v165, 0xffff0000, v166
	v_lshlrev_b32_e32 v166, 16, v167
	v_and_b32_e32 v167, 0xffff0000, v167
	v_add_u32_e32 v176, v229, v231
	s_waitcnt vmcnt(1)
	v_lshlrev_b32_e32 v206, 16, v172
	v_and_b32_e32 v207, 0xffff0000, v172
	v_lshlrev_b32_e32 v172, 16, v173
	v_and_b32_e32 v173, 0xffff0000, v173
	v_pk_mul_f32 v[206:207], v[140:141], v[206:207]
	v_pk_mul_f32 v[172:173], v[142:143], v[172:173]
	v_lshlrev_b32_e32 v208, 16, v174
	v_pk_fma_f32 v[168:169], v[146:147], v[168:169], v[172:173]
	v_pk_fma_f32 v[172:173], v[144:145], v[202:203], v[206:207]
	v_and_b32_e32 v209, 0xffff0000, v174
	v_lshlrev_b32_e32 v174, 16, v175
	v_and_b32_e32 v175, 0xffff0000, v175
	v_pk_fma_f32 v[160:161], v[148:149], v[160:161], v[172:173]
	v_pk_fma_f32 v[162:163], v[150:151], v[162:163], v[168:169]
	v_pk_mul_f32 v[152:153], v[152:153], v[160:161]
	v_pk_mul_f32 v[158:159], v[158:159], v[162:163]
	v_pk_mul_f32 v[160:161], v[128:129], v[208:209]
	v_pk_mul_f32 v[162:163], v[130:131], v[174:175]
	v_pk_fma_f32 v[160:161], v[132:133], v[204:205], v[160:161]
	v_pk_fma_f32 v[162:163], v[134:135], v[170:171], v[162:163]
	v_pk_fma_f32 v[160:161], v[136:137], v[164:165], v[160:161]
	v_pk_fma_f32 v[162:163], v[138:139], v[166:167], v[162:163]
	v_cvt_pk_bf16_f32 v152, v152, v153
	v_pk_mul_f32 v[162:163], v[154:155], v[162:163]
	v_pk_mul_f32 v[154:155], v[156:157], v[160:161]
	v_cvt_pk_bf16_f32 v153, v158, v159
	v_cvt_pk_bf16_f32 v154, v154, v155
	v_cvt_pk_bf16_f32 v155, v162, v163
	global_store_dwordx4 v199, v[152:155], s[34:35]
	v_add_u32_e32 v202, v230, v231
	s_nop 0
	v_add_u32_e32 v152, 0xfffff800, v176
	v_add_u32_e32 v153, 0xfffff000, v176
	v_cndmask_b32_e64 v152, v152, v176, s[46:47]
	v_cndmask_b32_e64 v153, v153, v176, s[46:47]
	global_load_dwordx4 v[168:171], v152, s[30:31]
	global_load_dwordx4 v[164:167], v153, s[30:31]
	v_add_u32_e32 v152, 0xfffff800, v202
	v_add_u32_e32 v153, 0xfffff000, v202
	global_load_dwordx4 v[172:175], v176, s[30:31]
	global_load_dwordx4 v[160:163], v202, s[30:31]
	global_load_dwordx4 v[156:159], v152, s[30:31]
	s_nop 0
	global_load_dwordx4 v[152:155], v153, s[30:31]
	ds_read_b32 v206, v227 offset:256
	s_waitcnt lgkmcnt(0)
	v_pk_mul_f32 v[208:209], v[58:59], v[206:207] op_sel_hi:[1,0]
	v_pk_mul_f32 v[210:211], v[56:57], v[206:207] op_sel_hi:[1,0]
	v_pk_mul_f32 v[204:205], v[50:51], v[206:207] op_sel_hi:[1,0]
	v_pk_mul_f32 v[206:207], v[48:49], v[206:207] op_sel_hi:[1,0]
	s_and_saveexec_b64 s[10:11], s[42:43]
	s_cbranch_execz .LBB0_173
	s_waitcnt vmcnt(4)
	v_lshlrev_b32_e32 v234, 16, v164
	v_and_b32_e32 v235, 0xffff0000, v164
	v_lshlrev_b32_e32 v164, 16, v165
	v_and_b32_e32 v165, 0xffff0000, v165
	v_lshlrev_b32_e32 v216, 16, v168
	v_and_b32_e32 v217, 0xffff0000, v168
	v_lshlrev_b32_e32 v168, 16, v169
	v_and_b32_e32 v169, 0xffff0000, v169
	v_pk_mul_f32 v[164:165], v[142:143], v[164:165]
	s_waitcnt vmcnt(3)
	v_lshlrev_b32_e32 v200, 16, v172
	v_and_b32_e32 v201, 0xffff0000, v172
	v_lshlrev_b32_e32 v172, 16, v173
	v_and_b32_e32 v173, 0xffff0000, v173
	v_pk_fma_f32 v[164:165], v[146:147], v[168:169], v[164:165]
	v_lshlrev_b32_e32 v236, 16, v166
	v_and_b32_e32 v237, 0xffff0000, v166
	v_lshlrev_b32_e32 v166, 16, v167
	v_and_b32_e32 v167, 0xffff0000, v167
	v_pk_fma_f32 v[164:165], v[150:151], v[172:173], v[164:165]
	v_lshlrev_b32_e32 v232, 16, v170
	v_and_b32_e32 v233, 0xffff0000, v170
	v_lshlrev_b32_e32 v170, 16, v171
	v_and_b32_e32 v171, 0xffff0000, v171
	v_pk_mul_f32 v[234:235], v[140:141], v[234:235]
	v_pk_mul_f32 v[208:209], v[208:209], v[164:165]
	v_pk_mul_f32 v[164:165], v[128:129], v[236:237]
	v_pk_mul_f32 v[166:167], v[130:131], v[166:167]
	v_lshlrev_b32_e32 v212, 16, v174
	v_and_b32_e32 v213, 0xffff0000, v174
	v_lshlrev_b32_e32 v174, 16, v175
	v_and_b32_e32 v175, 0xffff0000, v175
	v_pk_fma_f32 v[168:169], v[144:145], v[216:217], v[234:235]
	v_pk_fma_f32 v[166:167], v[134:135], v[170:171], v[166:167]
	v_pk_fma_f32 v[164:165], v[132:133], v[232:233], v[164:165]
	v_pk_fma_f32 v[168:169], v[148:149], v[200:201], v[168:169]
	v_pk_fma_f32 v[164:165], v[136:137], v[212:213], v[164:165]
	v_pk_fma_f32 v[166:167], v[138:139], v[174:175], v[166:167]
	v_pk_mul_f32 v[210:211], v[210:211], v[168:169]
	v_pk_mul_f32 v[204:205], v[204:205], v[166:167]
	v_pk_mul_f32 v[206:207], v[206:207], v[164:165]
	v_mov_b64_e32 v[200:201], 0x12d00000
	s_and_b32 s98, s2, 7
	s_mul_i32 s98, s98, 0xe00000
	v_add_u32_e32 v200, s98, v200

.LBB0_230:
	s_or_b64 exec, exec, s[0:1]
	v_readlane_b32 s56, v253, 32
	s_xor_b64 s[0:1], s[6:7], -1
	v_readlane_b32 s70, v253, 46
	v_readlane_b32 s71, v253, 47
	v_writelane_b32 v255, s0, 18
	s_mov_b64 s[6:7], s[70:71]
	s_waitcnt lgkmcnt(0)
	v_writelane_b32 v255, s1, 19
	s_barrier
	s_add_u32 s98, s6, 0x283780
	s_addc_u32 s99, s7, 0
	v_mov_b32_e32 v1, 0
	global_load_dword v1, v1, s[98:99] sc1
	s_waitcnt vmcnt(0)
	v_readfirstlane_b32 s98, v1
	s_nop 3
	s_cmp_eq_u32 s98, 0
	s_cselect_b32 s101, 1, 0
	s_add_u32 s8, s6, 0x12d00000
	v_mov_b32_e32 v24, v218
	s_movk_i32 s0, 0x100
	s_addc_u32 s9, s7, 0
	s_and_b32 s98, s2, 7
	s_mul_i32 s98, s98, 0xe00000
	s_add_u32 s8, s8, s98
	s_addc_u32 s9, s9, 0
	v_readlane_b32 s57, v253, 33
	v_cmp_gt_i32_e32 vcc, s0, v24
	v_readlane_b32 s58, v253, 34
	v_readlane_b32 s59, v253, 35
	v_readlane_b32 s60, v253, 36
	v_readlane_b32 s61, v253, 37
	v_readlane_b32 s62, v253, 38
	v_readlane_b32 s63, v253, 39
	v_readlane_b32 s64, v253, 40
	v_readlane_b32 s65, v253, 41
	v_readlane_b32 s66, v253, 42
	v_readlane_b32 s67, v253, 43
	v_readlane_b32 s68, v253, 44
	v_readlane_b32 s69, v253, 45
	s_and_saveexec_b64 s[0:1], vcc
	s_xor_b64 s[0:1], exec, s[0:1]
	s_cbranch_execz .LBB0_243
	v_lshlrev_b32_e32 v0, 3, v24
	v_and_b32_e32 v32, 0x3f8, v0
	v_lshlrev_b32_e32 v20, 2, v32
	global_load_dwordx4 v[0:3], v20, s[22:23] offset:16
	global_load_dwordx4 v[4:7], v20, s[22:23]
	global_load_dwordx4 v[8:11], v20, s[20:21] offset:16
	global_load_dwordx4 v[12:15], v20, s[20:21]
	global_load_dwordx4 v[16:19], v20, s[18:19] offset:16
	s_nop 0
	global_load_dwordx4 v[20:23], v20, s[18:19]
	s_add_u32 s12, s6, 0xa900000
	s_addc_u32 s13, s7, 0
	s_add_u32 s18, s6, 0xe900000
	s_addc_u32 s19, s7, 0
	v_ashrrev_i32_e32 v33, 7, v24
	s_mov_b64 s[20:21], s[2:3]
	s_branch .LBB0_234

.LBB0_561:
	s_and_b64 s[30:31], s[40:41], exec
	s_cselect_b32 s58, 0, 2
	s_add_u32 s30, s20, 0x13b00000
	s_addc_u32 s31, s21, 0
	s_and_b32 s98, s2, 7
	s_mul_i32 s98, s98, 0x1300000
	s_add_u32 s30, s30, s98
	s_addc_u32 s31, s31, 0
	s_add_u32 s34, s20, 0x300000
	s_addc_u32 s35, s21, 0
	s_add_i32 m0, s52, 0x18000
	v_lshl_add_u64 v[0:1], v[0:1], 0, s[12:13]
	s_waitcnt vmcnt(2)
	s_barrier
	global_load_lds_dwordx4 v[0:1], off
	v_lshl_add_u64 v[0:1], v[2:3], 0, s[12:13]
	s_add_i32 m0, s52, 0x1a000
	s_add_i32 s59, s52, 0x8000
	global_load_lds_dwordx4 v[0:1], off
	v_lshl_add_u64 v[0:1], v[8:9], 0, s[12:13]
	s_mov_b32 m0, s59
	s_add_i32 s60, s52, 0xa000
	global_load_lds_dwordx4 v[0:1], off
	v_lshl_add_u64 v[0:1], v[10:11], 0, s[12:13]
	s_mov_b32 m0, s60
	s_lshr_b32 s7, s7, 26
	global_load_lds_dwordx4 v[0:1], off
	s_add_i32 m0, s52, 0x1c000
	v_lshl_add_u64 v[0:1], v[4:5], 0, s[12:13]
	global_load_lds_dwordx4 v[0:1], off
	v_lshl_add_u64 v[0:1], v[6:7], 0, s[12:13]
	s_add_i32 m0, s52, 0x1e000
	v_and_b32_e32 v141, 15, v12
	global_load_lds_dwordx4 v[0:1], off
	v_bfe_u32 v1, v12, 4, 2
	s_add_i32 s7, s6, s7
	v_lshlrev_b32_e32 v0, 4, v1
	v_lshlrev_b32_e32 v3, 2, v12
	s_and_b32 s62, s8, 3
	s_ashr_i32 s68, s7, 6
	v_lshl_or_b32 v2, v141, 6, v0
	s_lshl_b32 s7, s9, 13
	v_and_b32_e32 v3, 32, v3
	s_lshl_b32 s66, s9, 6
	v_bitop3_b32 v4, v2, s7, v3 bitop3:0xde
	s_lshl_b32 s67, s62, 5
	s_lshl_b32 s7, s62, 12
	s_cmp_gt_i32 s6, 63
	s_cselect_b64 s[36:37], -1, 0
	s_add_i32 s63, s68, -2
	s_cmpk_lt_u32 s14, 0x100
	v_bitop3_b32 v153, v2, s7, v3 bitop3:0xde
	s_cselect_b64 s[6:7], -1, 0
	s_cmp_eq_u32 s62, 0
	s_cselect_b64 s[94:95], -1, 0
	s_lshl_b32 s8, s62, 2
	s_add_u32 s8, s20, s8
	s_addc_u32 s9, s21, 0
	s_add_u32 s14, s8, 0x200000
	s_mov_b64 s[42:43], s[40:41]
	s_addc_u32 s15, s9, 0
	v_writelane_b32 v254, s42, 40
	s_and_b64 s[8:9], s[42:43], exec
	s_cselect_b32 s8, 6, 5
	s_lshl_b32 s69, s16, 3
	v_lshlrev_b32_e32 v140, 3, v1
	v_cmp_eq_u32_e64 s[40:41], 0, v1
	v_lshlrev_b32_e32 v180, 6, v1
	v_cvt_f32_ubyte0_e32 v1, s69
	v_rcp_iflag_f32_e32 v1, v1
	v_writelane_b32 v253, s8, 50
	v_lshl_add_u64 v[2:3], s[20:21], 0, v[180:181]
	s_mov_b64 s[8:9], 0x400000
	v_mul_f32_e32 v1, 0x4f7ffffe, v1
	v_cvt_u32_f32_e32 v1, v1
	v_lshl_add_u64 v[142:143], v[2:3], 0, s[8:9]
	s_lshl_b32 s8, s16, 4
	s_or_b32 s8, s8, 1
	v_writelane_b32 v255, s8, 18
	s_sub_i32 s8, 0, s69
	v_readfirstlane_b32 s9, v1
	s_mul_i32 s8, s8, s9
	s_mul_hi_u32 s8, s9, s8
	v_mov_b32_e32 v1, v181
	s_add_i32 s70, s9, s8
	v_lshl_add_u64 v[2:3], s[20:21], 0, v[0:1]
	s_mov_b64 s[8:9], 0x12900000
	v_lshl_add_u64 v[144:145], v[2:3], 0, s[8:9]
	s_lshl_b32 s8, s62, 6
	s_add_u32 s8, s20, s8
	s_addc_u32 s9, s21, 0
	v_lshl_add_u64 v[0:1], s[8:9], 0, v[0:1]
	s_mov_b64 s[8:9], 0x13900000
	s_and_b32 s98, s2, 7
	s_mul_i32 s98, s98, 0x1400000
	s_add_u32 s8, s8, s98
	v_lshl_add_u64 v[146:147], v[0:1], 0, s[8:9]
	v_add_u32_e32 v0, v15, v13
	s_waitcnt vmcnt(6)
	v_add_lshl_u32 v180, v0, v14, 1
	v_add_u32_e32 v0, v18, v16
	v_lshl_add_u64 v[148:149], s[24:25], 0, v[180:181]
	v_add_lshl_u32 v180, v0, v17, 1
	s_mov_b32 s61, 0
	v_and_b32_e32 v155, 63, v12
	v_writelane_b32 v254, s43, 41
	s_mov_b32 s23, s65
	v_lshl_add_u64 v[150:151], s[24:25], 0, v[180:181]
	v_add_u32_e32 v157, 0, v4
	s_barrier
	s_branch .LBB0_564

.LBB0_779:
	s_or_b64 exec, exec, s[0:1]
	s_andn2_b64 vcc, exec, s[40:41]
	s_waitcnt lgkmcnt(0)
	s_barrier
	s_cbranch_vccnz .LBB0_830
	v_readlane_b32 s16, v253, 32
	v_readlane_b32 s18, v253, 34
	v_readlane_b32 s19, v253, 35
	v_readlane_b32 s20, v253, 36
	v_readlane_b32 s30, v253, 46
	v_readlane_b32 s31, v253, 47
	v_readlane_b32 s0, v255, 20
	s_mov_b64 s[18:19], s[30:31]
	s_movk_i32 s20, 0x100
	v_mov_b32_e32 v12, v218
	v_readlane_b32 s1, v255, 21
	s_and_b64 vcc, exec, s[0:1]
	v_readfirstlane_b32 s10, v12
	v_readlane_b32 s17, v253, 33
	v_readlane_b32 s21, v253, 37
	v_readlane_b32 s22, v253, 38
	v_readlane_b32 s23, v253, 39
	v_readlane_b32 s24, v253, 40
	v_readlane_b32 s25, v253, 41
	v_readlane_b32 s26, v253, 42
	v_readlane_b32 s27, v253, 43
	v_readlane_b32 s28, v253, 44
	v_readlane_b32 s29, v253, 45
	s_cbranch_vccnz .LBB0_805
	v_lshlrev_b32_e32 v0, 4, v12
	v_add_u32_e32 v1, 0x2000, v0
	v_ashrrev_i32_e32 v2, 31, v1
	v_lshrrev_b32_e32 v2, 22, v2
	v_add_u32_e32 v2, v1, v2
	v_ashrrev_i32_e32 v2, 10, v2
	v_mul_i32_i24_e32 v3, 0x400, v2
	v_sub_u32_e32 v1, v1, v3
	v_lshrrev_b32_e32 v3, 4, v1
	v_bitop3_b32 v1, v3, v1, 32 bitop3:0x6c
	v_ashrrev_i32_e32 v3, 31, v1
	v_lshrrev_b32_e32 v3, 26, v3
	v_add_u32_e32 v3, v1, v3
	v_lshlrev_b32_e32 v5, 3, v2
	v_ashrrev_i32_e32 v4, 6, v3
	v_and_b32_e32 v5, -16, v5
	v_lshlrev_b32_e32 v2, 5, v2
	v_add_u32_e32 v5, v4, v5
	v_and_b32_e32 v13, 32, v2
	v_and_b32_e32 v2, 0xc0, v3
	v_and_b32_e32 v4, 3, v4
	s_mov_b32 s8, 0x7fffffe0
	v_lshrrev_b32_e32 v6, 2, v5
	v_lshlrev_b32_e32 v7, 1, v5
	v_sub_u32_e32 v1, v1, v2
	v_and_or_b32 v4, v5, s8, v4
	v_and_b32_e32 v6, 4, v6
	v_and_b32_e32 v7, 24, v7
	v_ashrrev_i16_sdwa v1, v205, sext(v1) dst_sel:DWORD dst_unused:UNUSED_PAD src0_sel:DWORD src1_sel:BYTE_0
	v_or3_b32 v4, v4, v6, v7
	v_bfe_i32 v14, v1, 0, 16
	v_mul_lo_u32 v4, v4, s20
	v_add_u32_e32 v1, v13, v14
	v_mul_lo_u32 v15, v5, s20
	v_add_lshl_u32 v128, v4, v1, 1
	v_add_lshl_u32 v130, v1, v15, 1
	v_bfe_i32 v1, v12, 27, 1
	v_lshrrev_b32_e32 v1, 22, v1
	v_add_u32_e32 v1, v0, v1
	v_and_b32_e32 v1, 0xfffffc00, v1
	v_sub_u32_e32 v0, v0, v1
	v_lshrrev_b32_e32 v1, 4, v0
	v_ashrrev_i32_e32 v3, 31, v12
	v_bitop3_b32 v0, v1, v0, 32 bitop3:0x6c
	v_lshrrev_b32_e32 v3, 26, v3
	v_ashrrev_i32_e32 v1, 31, v0
	v_add_u32_e32 v3, v12, v3
	s_add_u32 s4, s18, 0x13900000
	v_lshrrev_b32_e32 v1, 26, v1
	v_ashrrev_i32_e32 v3, 6, v3
	s_addc_u32 s33, s19, 0
	s_and_b32 s98, s2, 7
	s_mul_i32 s98, s98, 0x1400000
	s_add_u32 s4, s4, s98
	s_addc_u32 s33, s33, 0
	v_add_u32_e32 v1, v0, v1
	v_lshlrev_b32_e32 v4, 3, v3
	s_add_u32 s34, s18, 0x7f00000
	v_ashrrev_i32_e32 v2, 6, v1
	v_and_b32_e32 v4, -16, v4
	s_addc_u32 s35, s19, 0
	s_ashr_i32 s21, s20, 31
	v_add_u32_e32 v4, v2, v4
	v_and_b32_e32 v2, 3, v2
	s_lshl_b64 s[6:7], s[20:21], 9
	v_and_or_b32 v2, v4, s8, v2
	v_readlane_b32 s8, v254, 53
	s_mul_i32 s8, s6, s8
	s_mul_hi_u32 s9, s6, s95
	s_add_i32 s14, s9, s8
	s_lshr_b64 s[8:9], s[20:21], 23
	v_readlane_b32 s24, v254, 50
	s_mul_i32 s9, s8, s95
	v_readlane_b32 s25, v254, 51
	v_and_b32_e32 v1, 0xc0, v1
	s_add_i32 s14, s14, s9
	s_mul_i32 s9, s6, s25
	s_mul_hi_u32 s16, s6, s24
	s_ashr_i32 s11, s10, 6
	v_lshrrev_b32_e32 v5, 2, v4
	v_lshlrev_b32_e32 v6, 1, v4
	v_sub_u32_e32 v0, v0, v1
	s_add_i32 s9, s16, s9
	s_mul_i32 s8, s8, s24
	s_ashr_i32 s22, s10, 8
	s_lshl_b64 s[0:1], s[20:21], 8
	s_lshl_b32 s36, s11, 10
	v_and_b32_e32 v5, 4, v5
	v_and_b32_e32 v6, 24, v6
	v_lshlrev_b32_e32 v3, 5, v3
	v_ashrrev_i16_sdwa v0, v205, sext(v0) dst_sel:DWORD dst_unused:UNUSED_PAD src0_sel:DWORD src1_sel:BYTE_0
	s_add_i32 s9, s9, s8
	s_mul_i32 s8, s6, s24
	v_or3_b32 v2, v2, v5, v6
	v_and_b32_e32 v16, 32, v3
	v_bfe_i32 v17, v0, 0, 16
	s_add_u32 s30, s34, s8
	v_mul_lo_u32 v2, v2, s20
	v_add_u32_e32 v0, v16, v17
	s_addc_u32 s31, s35, s9
	s_add_i32 s37, s36, 0
	v_add_lshl_u32 v132, v2, v0, 1
	s_add_i32 m0, s37, 0x10000
	s_mul_i32 s15, s6, s95
	global_load_lds_dwordx4 v132, s[30:31]
	s_add_i32 m0, s37, 0x12000
	s_add_u32 s8, s30, s0
	global_load_lds_dwordx4 v128, s[30:31]
	s_addc_u32 s9, s31, s1
	s_add_i32 m0, s37, 0x14000
	v_mul_lo_u32 v18, v4, s20
	global_load_lds_dwordx4 v132, s[8:9]
	s_add_i32 m0, s37, 0x16000
	s_add_u32 s16, s4, s15
	v_mov_b32_e32 v133, v181
	v_mov_b32_e32 v129, v181
	s_addc_u32 s17, s33, s14
	s_add_i32 s38, s37, 0x2000
	v_add_lshl_u32 v134, v0, v18, 1
	v_lshl_add_u64 v[4:5], s[8:9], 0, v[132:133]
	v_lshl_add_u64 v[6:7], s[8:9], 0, v[128:129]
	global_load_lds_dwordx4 v128, s[8:9]
	s_mov_b32 m0, s37
	s_add_u32 s8, s16, s0
	global_load_lds_dwordx4 v134, s[16:17]
	s_mov_b32 m0, s38
	s_addc_u32 s9, s17, s1
	s_add_i32 s39, s37, 0x4000
	global_load_lds_dwordx4 v130, s[16:17]
	s_mov_b32 m0, s39
	s_add_i32 s44, s37, 0x6000
	global_load_lds_dwordx4 v134, s[8:9]
	s_mov_b32 m0, s44
	v_mov_b32_e32 v135, v181
	global_load_lds_dwordx4 v130, s[8:9]
	v_mov_b32_e32 v131, v181
	s_cmp_eq_u32 s22, 1
	v_lshl_add_u64 v[0:1], s[30:31], 0, v[132:133]
	v_lshl_add_u64 v[2:3], s[30:31], 0, v[128:129]
	v_lshl_add_u64 v[8:9], s[16:17], 0, v[134:135]
	v_lshl_add_u64 v[10:11], s[16:17], 0, v[130:131]
	s_cselect_b64 s[8:9], -1, 0
	s_cmp_lg_u32 s22, 1
	s_cbranch_scc1 .LBB0_783
	s_barrier

.LBB0_805:
	v_readlane_b32 s16, v253, 32
	v_readlane_b32 s18, v253, 34
	v_readlane_b32 s19, v253, 35
	v_readlane_b32 s30, v253, 46
	v_readlane_b32 s31, v253, 47
	v_readlane_b32 s0, v255, 20
	s_mov_b64 s[18:19], s[30:31]
	s_movk_i32 s16, 0x100
	v_mov_b32_e32 v18, v218
	v_readlane_b32 s1, v255, 21
	s_and_b64 vcc, exec, s[0:1]
	v_readfirstlane_b32 s10, v18
	v_readlane_b32 s17, v253, 33
	v_readlane_b32 s20, v253, 36
	v_readlane_b32 s21, v253, 37
	v_readlane_b32 s22, v253, 38
	v_readlane_b32 s23, v253, 39
	v_readlane_b32 s24, v253, 40
	v_readlane_b32 s25, v253, 41
	v_readlane_b32 s26, v253, 42
	v_readlane_b32 s27, v253, 43
	v_readlane_b32 s28, v253, 44
	v_readlane_b32 s29, v253, 45
	s_cbranch_vccnz .LBB0_830
	v_lshlrev_b32_e32 v0, 4, v18
	v_add_u32_e32 v1, 0x2000, v0
	v_ashrrev_i32_e32 v2, 31, v1
	v_lshrrev_b32_e32 v2, 22, v2
	v_add_u32_e32 v2, v1, v2
	v_ashrrev_i32_e32 v2, 10, v2
	v_mul_i32_i24_e32 v3, 0x400, v2
	v_sub_u32_e32 v1, v1, v3
	v_lshrrev_b32_e32 v3, 4, v1
	v_bitop3_b32 v1, v3, v1, 32 bitop3:0x6c
	v_ashrrev_i32_e32 v3, 31, v1
	v_lshrrev_b32_e32 v3, 26, v3
	v_add_u32_e32 v3, v1, v3
	v_lshlrev_b32_e32 v5, 3, v2
	v_ashrrev_i32_e32 v4, 6, v3
	v_and_b32_e32 v5, -16, v5
	v_lshlrev_b32_e32 v2, 5, v2
	v_add_u32_e32 v5, v4, v5
	v_and_b32_e32 v12, 32, v2
	v_and_b32_e32 v2, 0xc0, v3
	v_and_b32_e32 v4, 3, v4
	s_mov_b32 s8, 0x7fffffe0
	v_lshrrev_b32_e32 v6, 2, v5
	v_lshlrev_b32_e32 v7, 1, v5
	v_sub_u32_e32 v1, v1, v2
	v_and_or_b32 v4, v5, s8, v4
	v_and_b32_e32 v6, 4, v6
	v_and_b32_e32 v7, 24, v7
	v_ashrrev_i16_sdwa v1, v205, sext(v1) dst_sel:DWORD dst_unused:UNUSED_PAD src0_sel:DWORD src1_sel:BYTE_0
	v_or3_b32 v4, v4, v6, v7
	v_bfe_i32 v13, v1, 0, 16
	v_mul_lo_u32 v4, v4, s16
	v_add_u32_e32 v1, v12, v13
	v_mul_lo_u32 v14, v5, s16
	v_add_lshl_u32 v128, v4, v1, 1
	v_add_lshl_u32 v130, v1, v14, 1
	v_bfe_i32 v1, v18, 27, 1
	v_lshrrev_b32_e32 v1, 22, v1
	v_add_u32_e32 v1, v0, v1
	v_and_b32_e32 v1, 0xfffffc00, v1
	v_sub_u32_e32 v0, v0, v1
	v_lshrrev_b32_e32 v1, 4, v0
	v_ashrrev_i32_e32 v3, 31, v18
	v_bitop3_b32 v0, v1, v0, 32 bitop3:0x6c
	v_lshrrev_b32_e32 v3, 26, v3
	v_ashrrev_i32_e32 v1, 31, v0
	v_add_u32_e32 v3, v18, v3
	s_add_u32 s4, s18, 0x7f80000
	v_lshrrev_b32_e32 v1, 26, v1
	v_ashrrev_i32_e32 v3, 6, v3
	s_addc_u32 s30, s19, 0
	v_add_u32_e32 v1, v0, v1
	v_lshlrev_b32_e32 v4, 3, v3
	s_add_u32 s31, s18, 0x13900000
	v_ashrrev_i32_e32 v2, 6, v1
	v_and_b32_e32 v4, -16, v4
	s_addc_u32 s33, s19, 0
	s_and_b32 s98, s2, 7
	s_mul_i32 s98, s98, 0x1400000
	s_add_u32 s31, s31, s98
	s_addc_u32 s33, s33, 0
	s_ashr_i32 s17, s16, 31
	v_add_u32_e32 v4, v2, v4
	v_and_b32_e32 v2, 3, v2
	s_lshl_b64 s[6:7], s[16:17], 9
	v_and_or_b32 v2, v4, s8, v2
	v_readlane_b32 s8, v255, 15
	v_readlane_b32 s15, v255, 14
	s_mul_i32 s8, s6, s8
	s_mul_hi_u32 s9, s6, s15
	s_add_i32 s14, s9, s8
	s_lshr_b64 s[8:9], s[16:17], 23
	s_mul_i32 s9, s8, s15
	s_add_i32 s14, s14, s9
	v_readlane_b32 s9, v255, 17
	v_readlane_b32 s22, v255, 16
	v_and_b32_e32 v1, 0xc0, v1
	s_mul_i32 s9, s6, s9
	s_mul_hi_u32 s21, s6, s22
	s_ashr_i32 s11, s10, 6
	v_lshrrev_b32_e32 v5, 2, v4
	v_lshlrev_b32_e32 v6, 1, v4
	v_sub_u32_e32 v0, v0, v1
	s_add_i32 s9, s21, s9
	s_mul_i32 s8, s8, s22
	s_ashr_i32 s20, s10, 8
	s_lshl_b64 s[0:1], s[16:17], 8
	s_lshl_b32 s34, s11, 10
	v_and_b32_e32 v5, 4, v5
	v_and_b32_e32 v6, 24, v6
	v_lshlrev_b32_e32 v3, 5, v3
	v_ashrrev_i16_sdwa v0, v205, sext(v0) dst_sel:DWORD dst_unused:UNUSED_PAD src0_sel:DWORD src1_sel:BYTE_0
	s_add_i32 s9, s9, s8
	s_mul_i32 s8, s6, s22
	v_or3_b32 v2, v2, v5, v6
	v_and_b32_e32 v15, 32, v3
	v_bfe_i32 v16, v0, 0, 16
	s_add_u32 s28, s31, s8
	v_mul_lo_u32 v2, v2, s16
	v_add_u32_e32 v0, v15, v16
	s_addc_u32 s29, s33, s9
	s_add_i32 s35, s34, 0
	v_add_lshl_u32 v132, v2, v0, 1
	s_add_i32 m0, s35, 0x10000
	s_mul_i32 s15, s6, s15
	global_load_lds_dwordx4 v132, s[28:29]
	s_add_i32 m0, s35, 0x12000
	s_add_u32 s8, s28, s0
	global_load_lds_dwordx4 v128, s[28:29]
	s_addc_u32 s9, s29, s1
	s_add_i32 m0, s35, 0x14000
	v_mul_lo_u32 v17, v4, s16
	global_load_lds_dwordx4 v132, s[8:9]
	s_add_i32 m0, s35, 0x16000
	s_add_u32 s26, s4, s15
	v_mov_b32_e32 v133, v181
	v_mov_b32_e32 v129, v181
	s_addc_u32 s27, s30, s14
	s_add_i32 s36, s35, 0x2000
	v_add_lshl_u32 v134, v0, v17, 1
	v_lshl_add_u64 v[4:5], s[8:9], 0, v[132:133]
	v_lshl_add_u64 v[6:7], s[8:9], 0, v[128:129]
	global_load_lds_dwordx4 v128, s[8:9]
	s_mov_b32 m0, s35
	s_add_u32 s8, s26, s0
	global_load_lds_dwordx4 v134, s[26:27]
	s_mov_b32 m0, s36
	s_addc_u32 s9, s27, s1
	s_add_i32 s37, s35, 0x4000
	global_load_lds_dwordx4 v130, s[26:27]
	s_mov_b32 m0, s37
	s_add_i32 s38, s35, 0x6000
	global_load_lds_dwordx4 v134, s[8:9]
	s_mov_b32 m0, s38
	v_mov_b32_e32 v135, v181
	global_load_lds_dwordx4 v130, s[8:9]
	v_mov_b32_e32 v131, v181
	s_cmp_eq_u32 s20, 1
	v_lshl_add_u64 v[0:1], s[28:29], 0, v[132:133]
	v_lshl_add_u64 v[2:3], s[28:29], 0, v[128:129]
	v_lshl_add_u64 v[8:9], s[26:27], 0, v[134:135]
	v_lshl_add_u64 v[10:11], s[26:27], 0, v[130:131]
	s_cselect_b64 s[8:9], -1, 0
	s_cmp_lg_u32 s20, 1
	s_cbranch_scc1 .LBB0_808
	s_barrier

.LBB0_830:
	v_readlane_b32 s16, v253, 32
	v_readlane_b32 s17, v253, 33
	v_readlane_b32 s22, v253, 38
	v_readlane_b32 s30, v253, 46
	v_readlane_b32 s31, v253, 47
	v_readlane_b32 s0, v253, 56
	s_mov_b64 s[16:17], s[30:31]
	s_movk_i32 s22, 0x180
	v_mov_b32_e32 v12, v218
	v_readlane_b32 s1, v253, 57
	s_andn2_b64 vcc, exec, s[0:1]
	v_readfirstlane_b32 s10, v12
	v_readlane_b32 s18, v253, 34
	v_readlane_b32 s19, v253, 35
	v_readlane_b32 s20, v253, 36
	v_readlane_b32 s21, v253, 37
	v_readlane_b32 s23, v253, 39
	v_readlane_b32 s24, v253, 40
	v_readlane_b32 s25, v253, 41
	v_readlane_b32 s26, v253, 42
	v_readlane_b32 s27, v253, 43
	v_readlane_b32 s28, v253, 44
	v_readlane_b32 s29, v253, 45
	s_cbranch_vccnz .LBB0_883
	v_lshlrev_b32_e32 v0, 4, v12
	v_add_u32_e32 v1, 0x2000, v0
	v_ashrrev_i32_e32 v2, 31, v1
	v_lshrrev_b32_e32 v2, 22, v2
	v_add_u32_e32 v2, v1, v2
	v_ashrrev_i32_e32 v2, 10, v2
	v_mul_i32_i24_e32 v3, 0x400, v2
	v_sub_u32_e32 v1, v1, v3
	v_lshrrev_b32_e32 v3, 4, v1
	v_bitop3_b32 v1, v3, v1, 32 bitop3:0x6c
	v_ashrrev_i32_e32 v3, 31, v1
	s_add_u32 s4, s16, 0x13b00000
	v_readlane_b32 s0, v253, 54
	v_lshrrev_b32_e32 v3, 26, v3
	s_addc_u32 s33, s17, 0
	s_and_b32 s98, s2, 7
	s_mul_i32 s98, s98, 0x1300000
	s_add_u32 s4, s4, s98
	s_addc_u32 s33, s33, 0
	s_mul_i32 s0, s0, 0x120000
	v_add_u32_e32 v3, v1, v3
	v_lshlrev_b32_e32 v5, 3, v2
	v_readlane_b32 s1, v253, 55
	s_add_u32 s0, s16, s0
	v_ashrrev_i32_e32 v4, 6, v3
	v_and_b32_e32 v5, -16, v5
	v_lshlrev_b32_e32 v2, 5, v2
	s_addc_u32 s1, s17, 0
	v_add_u32_e32 v5, v4, v5
	v_and_b32_e32 v13, 32, v2
	v_and_b32_e32 v2, 0xc0, v3
	s_add_u32 s36, s0, 0x8000000
	v_and_b32_e32 v4, 3, v4
	s_mov_b32 s0, 0x7fffffe0
	v_lshrrev_b32_e32 v6, 2, v5
	v_lshlrev_b32_e32 v7, 1, v5
	v_sub_u32_e32 v1, v1, v2
	v_and_or_b32 v4, v5, s0, v4
	v_and_b32_e32 v6, 4, v6
	v_and_b32_e32 v7, 24, v7
	v_ashrrev_i16_sdwa v1, v205, sext(v1) dst_sel:DWORD dst_unused:UNUSED_PAD src0_sel:DWORD src1_sel:BYTE_0
	v_or3_b32 v4, v4, v6, v7
	v_bfe_i32 v14, v1, 0, 16
	v_mul_lo_u32 v4, v4, s22
	v_add_u32_e32 v1, v13, v14
	v_mul_lo_u32 v15, v5, s22
	v_add_lshl_u32 v128, v4, v1, 1
	v_add_lshl_u32 v130, v1, v15, 1
	v_bfe_i32 v1, v12, 27, 1
	v_lshrrev_b32_e32 v1, 22, v1
	v_add_u32_e32 v1, v0, v1
	v_and_b32_e32 v1, 0xfffffc00, v1
	v_sub_u32_e32 v0, v0, v1
	v_lshrrev_b32_e32 v1, 4, v0
	v_ashrrev_i32_e32 v3, 31, v12
	v_bitop3_b32 v0, v1, v0, 32 bitop3:0x6c
	v_lshrrev_b32_e32 v3, 26, v3
	v_ashrrev_i32_e32 v1, 31, v0
	v_add_u32_e32 v3, v12, v3
	v_lshrrev_b32_e32 v1, 26, v1
	v_ashrrev_i32_e32 v3, 6, v3
	v_add_u32_e32 v1, v0, v1
	v_lshlrev_b32_e32 v4, 3, v3
	v_ashrrev_i32_e32 v2, 6, v1
	v_and_b32_e32 v4, -16, v4
	s_addc_u32 s37, s1, 0
	s_ashr_i32 s23, s22, 31
	v_add_u32_e32 v4, v2, v4
	v_and_b32_e32 v2, 3, v2
	s_lshl_b64 s[8:9], s[22:23], 9
	v_and_or_b32 v2, v4, s0, v2
	v_readlane_b32 s0, v255, 11
	v_readlane_b32 s15, v254, 38
	s_mul_i32 s0, s8, s0
	s_mul_hi_u32 s1, s8, s15
	s_add_i32 s14, s1, s0
	s_lshr_b64 s[0:1], s[22:23], 23
	v_readlane_b32 s20, v255, 12
	s_mul_i32 s1, s0, s15
	v_readlane_b32 s21, v255, 13
	v_and_b32_e32 v1, 0xc0, v1
	s_add_i32 s14, s14, s1
	s_mul_i32 s1, s8, s21
	s_mul_hi_u32 s18, s8, s20
	s_ashr_i32 s24, s10, 6
	v_lshrrev_b32_e32 v5, 2, v4
	v_lshlrev_b32_e32 v6, 1, v4
	v_sub_u32_e32 v0, v0, v1
	s_add_i32 s1, s18, s1
	s_mul_i32 s0, s0, s20
	s_ashr_i32 s11, s10, 8
	s_lshl_b64 s[6:7], s[22:23], 8
	s_lshl_b32 s38, s24, 10
	v_and_b32_e32 v5, 4, v5
	v_and_b32_e32 v6, 24, v6
	v_lshlrev_b32_e32 v3, 5, v3
	v_ashrrev_i16_sdwa v0, v205, sext(v0) dst_sel:DWORD dst_unused:UNUSED_PAD src0_sel:DWORD src1_sel:BYTE_0
	s_add_i32 s1, s1, s0
	s_mul_i32 s0, s8, s20
	v_or3_b32 v2, v2, v5, v6
	v_and_b32_e32 v16, 32, v3
	v_bfe_i32 v17, v0, 0, 16
	s_add_u32 s30, s36, s0
	v_mul_lo_u32 v2, v2, s22
	v_add_u32_e32 v0, v16, v17
	s_addc_u32 s31, s37, s1
	s_add_i32 s39, s38, 0
	v_add_lshl_u32 v132, v2, v0, 1
	s_add_i32 m0, s39, 0x10000
	s_mul_i32 s15, s8, s15
	global_load_lds_dwordx4 v132, s[30:31]
	s_add_i32 m0, s39, 0x12000
	s_add_u32 s0, s30, s6
	global_load_lds_dwordx4 v128, s[30:31]
	s_addc_u32 s1, s31, s7
	s_add_i32 m0, s39, 0x14000
	v_mov_b32_e32 v133, v181
	v_mov_b32_e32 v129, v181
	global_load_lds_dwordx4 v132, s[0:1]
	s_add_i32 m0, s39, 0x16000
	v_mul_lo_u32 v18, v4, s22
	v_lshl_add_u64 v[4:5], s[0:1], 0, v[132:133]
	v_lshl_add_u64 v[6:7], s[0:1], 0, v[128:129]
	global_load_lds_dwordx4 v128, s[0:1]
	s_add_u32 s0, s4, s15
	s_addc_u32 s1, s33, s14
	s_add_i32 s44, s39, 0x2000
	v_add_lshl_u32 v134, v0, v18, 1
	s_mov_b32 m0, s39
	s_add_u32 s14, s0, s6
	global_load_lds_dwordx4 v134, s[0:1]
	s_mov_b32 m0, s44
	s_addc_u32 s15, s1, s7
	s_add_i32 s45, s39, 0x4000
	global_load_lds_dwordx4 v130, s[0:1]
	s_mov_b32 m0, s45
	s_add_i32 s46, s39, 0x6000
	global_load_lds_dwordx4 v134, s[14:15]
	s_mov_b32 m0, s46
	v_mov_b32_e32 v135, v181
	global_load_lds_dwordx4 v130, s[14:15]
	v_mov_b32_e32 v131, v181
	s_cmp_eq_u32 s11, 1
	v_lshl_add_u64 v[0:1], s[30:31], 0, v[132:133]
	v_lshl_add_u64 v[2:3], s[30:31], 0, v[128:129]
	v_lshl_add_u64 v[8:9], s[0:1], 0, v[134:135]
	v_lshl_add_u64 v[10:11], s[0:1], 0, v[130:131]
	s_cselect_b64 s[14:15], -1, 0
	s_cmp_lg_u32 s11, 1
	s_cbranch_scc1 .LBB0_833
	s_barrier
.LBB0_833:
	s_add_u32 s18, s16, 0x300000
	s_addc_u32 s19, s17, 0
	s_add_u32 s20, s16, 0x12d00000
	s_addc_u32 s21, s17, 0
	s_and_b32 s98, s2, 7
	s_mul_i32 s98, s98, 0xa00000
	s_add_u32 s20, s20, s98
	s_addc_u32 s21, s21, 0
	s_add_i32 m0, s39, 0x18000
	v_lshl_add_u64 v[0:1], v[0:1], 0, s[12:13]
	s_waitcnt vmcnt(2)
	s_barrier
	global_load_lds_dwordx4 v[0:1], off
	v_lshl_add_u64 v[0:1], v[2:3], 0, s[12:13]
	s_add_i32 m0, s39, 0x1a000
	s_add_i32 s47, s39, 0x8000
	global_load_lds_dwordx4 v[0:1], off
	v_lshl_add_u64 v[0:1], v[8:9], 0, s[12:13]
	s_mov_b32 m0, s47
	s_add_i32 s48, s39, 0xa000
	global_load_lds_dwordx4 v[0:1], off
	v_lshl_add_u64 v[0:1], v[10:11], 0, s[12:13]
	s_mov_b32 m0, s48
	v_and_b32_e32 v137, 15, v12
	global_load_lds_dwordx4 v[0:1], off
	s_add_i32 m0, s39, 0x1c000
	v_lshl_add_u64 v[0:1], v[4:5], 0, s[12:13]
	global_load_lds_dwordx4 v[0:1], off
	v_lshl_add_u64 v[0:1], v[6:7], 0, s[12:13]
	s_add_i32 m0, s39, 0x1e000
	s_lshr_b32 s23, s23, 26
	global_load_lds_dwordx4 v[0:1], off
	v_bfe_u32 v0, v12, 4, 2
	v_lshlrev_b32_e32 v1, 4, v0
	v_lshlrev_b32_e32 v2, 2, v12
	s_and_b32 s26, s24, 3
	s_add_i32 s23, s22, s23
	s_lshl_b32 s52, s11, 6
	v_lshl_or_b32 v1, v137, 6, v1
	s_lshl_b32 s11, s11, 13
	v_and_b32_e32 v2, 32, v2
	s_ashr_i32 s49, s23, 6
	v_bitop3_b32 v3, v1, s11, v2 bitop3:0xde
	s_lshl_b32 s56, s26, 5
	s_lshl_b32 s11, s26, 12
	s_cmp_gt_i32 s22, 63
	s_cselect_b64 s[22:23], -1, 0
	s_add_i32 s57, s49, -2
	v_lshlrev_b32_e32 v180, 6, v0
	v_lshlrev_b32_e32 v136, 3, v0
	s_waitcnt vmcnt(0)
	v_bitop3_b32 v164, v1, s11, v2 bitop3:0xde
	s_cmpk_lt_u32 s10, 0x100
	v_lshl_add_u64 v[0:1], s[16:17], 0, v[180:181]
	s_mov_b64 s[10:11], 0x400000
	v_lshl_add_u64 v[138:139], v[0:1], 0, s[10:11]
	v_add_u32_e32 v0, v18, v16
	s_waitcnt vmcnt(6)
	v_add_lshl_u32 v180, v0, v17, 1
	v_add_u32_e32 v0, v15, v13
	v_lshl_add_u64 v[140:141], s[6:7], 0, v[180:181]
	v_add_lshl_u32 v180, v0, v14, 1
	s_cselect_b64 s[24:25], -1, 0
	v_and_b32_e32 v165, 63, v12
	s_or_b32 s58, s26, -16
	v_lshl_add_u64 v[142:143], s[6:7], 0, v[180:181]
	s_mov_b32 s59, 0
	v_add_u32_e32 v166, 0, v3
	v_readlane_b32 s62, v255, 9
	v_readlane_b32 s34, v254, 38
	s_barrier
	s_branch .LBB0_836

.LBB0_935:
	s_or_b64 exec, exec, s[0:1]
	v_readlane_b32 s16, v253, 32
	v_readlane_b32 s0, v254, 42
	v_readlane_b32 s30, v253, 46
	v_readlane_b32 s31, v253, 47
	v_readlane_b32 s1, v254, 43
	s_mov_b64 s[6:7], s[30:31]
	s_andn2_b64 vcc, exec, s[0:1]
	s_waitcnt lgkmcnt(0)
	s_barrier
	v_readlane_b32 s17, v253, 33
	v_readlane_b32 s18, v253, 34
	v_readlane_b32 s19, v253, 35
	v_readlane_b32 s20, v253, 36
	v_readlane_b32 s21, v253, 37
	v_readlane_b32 s22, v253, 38
	v_readlane_b32 s23, v253, 39
	v_readlane_b32 s24, v253, 40
	v_readlane_b32 s25, v253, 41
	v_readlane_b32 s26, v253, 42
	v_readlane_b32 s27, v253, 43
	v_readlane_b32 s28, v253, 44
	v_readlane_b32 s29, v253, 45
	s_cbranch_vccnz .LBB0_983
	s_add_u32 s8, s6, 0x12d00000
	s_addc_u32 s9, s7, 0
	s_and_b32 s98, s2, 7
	s_mul_i32 s98, s98, 0xa00000
	s_add_u32 s8, s8, s98
	s_addc_u32 s9, s9, 0
	s_add_u32 s4, s6, 0xa900000
	s_addc_u32 s33, s7, 0
	s_add_u32 s44, s6, 0x12900000
	s_addc_u32 s45, s7, 0
	s_add_u32 s46, s6, 0xe900000
	s_addc_u32 s47, s7, 0
	s_add_u32 s14, s6, 0x13900000
	s_addc_u32 s15, s7, 0
	s_and_b32 s98, s2, 7
	s_mul_i32 s98, s98, 0xe00000
	s_add_u32 s14, s14, s98
	s_addc_u32 s15, s15, 0
	v_readlane_b32 s48, v255, 10
	s_and_b32 s100, s2, 7
	s_lshl_b32 s100, s100, 5
	s_add_i32 s48, s48, s100
	s_add_i32 s100, s48, 64
	s_branch .LBB0_938

.LBB0_1035:
	s_or_b64 exec, exec, s[0:1]
	v_readlane_b32 s16, v253, 32
	v_readlane_b32 s30, v253, 46
	v_readlane_b32 s31, v253, 47
	v_readlane_b32 s6, v255, 20
	s_mov_b64 s[0:1], s[30:31]
	s_movk_i32 s16, 0x400
	v_mov_b32_e32 v18, v218
	v_readlane_b32 s7, v255, 21
	s_waitcnt lgkmcnt(0)
	s_barrier
	s_and_b64 vcc, exec, s[6:7]
	v_readfirstlane_b32 s10, v18
	v_readlane_b32 s17, v253, 33
	v_readlane_b32 s18, v253, 34
	v_readlane_b32 s19, v253, 35
	v_readlane_b32 s20, v253, 36
	v_readlane_b32 s21, v253, 37
	v_readlane_b32 s22, v253, 38
	v_readlane_b32 s23, v253, 39
	v_readlane_b32 s24, v253, 40
	v_readlane_b32 s25, v253, 41
	v_readlane_b32 s26, v253, 42
	v_readlane_b32 s27, v253, 43
	v_readlane_b32 s28, v253, 44
	v_readlane_b32 s29, v253, 45
	s_cbranch_vccnz .LBB0_1076
	v_lshlrev_b32_e32 v0, 4, v18
	v_add_u32_e32 v1, 0x2000, v0
	v_ashrrev_i32_e32 v2, 31, v1
	v_lshrrev_b32_e32 v2, 22, v2
	v_add_u32_e32 v2, v1, v2
	v_ashrrev_i32_e32 v2, 10, v2
	v_mul_i32_i24_e32 v3, 0x400, v2
	v_sub_u32_e32 v1, v1, v3
	v_lshrrev_b32_e32 v3, 4, v1
	v_bitop3_b32 v1, v3, v1, 32 bitop3:0x6c
	v_ashrrev_i32_e32 v3, 31, v1
	v_lshrrev_b32_e32 v3, 26, v3
	v_add_u32_e32 v3, v1, v3
	v_lshlrev_b32_e32 v5, 3, v2
	v_ashrrev_i32_e32 v4, 6, v3
	v_and_b32_e32 v5, -16, v5
	v_lshlrev_b32_e32 v2, 5, v2
	v_add_u32_e32 v5, v4, v5
	v_and_b32_e32 v12, 32, v2
	v_and_b32_e32 v2, 0xc0, v3
	v_and_b32_e32 v4, 3, v4
	s_mov_b32 s14, 0x7fffffe0
	v_lshrrev_b32_e32 v6, 2, v5
	v_lshlrev_b32_e32 v7, 1, v5
	v_sub_u32_e32 v1, v1, v2
	v_and_or_b32 v4, v5, s14, v4
	v_and_b32_e32 v6, 4, v6
	v_and_b32_e32 v7, 24, v7
	v_ashrrev_i16_sdwa v1, v205, sext(v1) dst_sel:DWORD dst_unused:UNUSED_PAD src0_sel:DWORD src1_sel:BYTE_0
	v_or3_b32 v4, v4, v6, v7
	v_bfe_i32 v13, v1, 0, 16
	v_mul_lo_u32 v4, v4, s16
	v_add_u32_e32 v1, v12, v13
	v_mul_lo_u32 v14, v5, s16
	v_add_lshl_u32 v156, v4, v1, 1
	v_add_lshl_u32 v158, v1, v14, 1
	v_bfe_i32 v1, v18, 27, 1
	v_lshrrev_b32_e32 v1, 22, v1
	v_add_u32_e32 v1, v0, v1
	v_and_b32_e32 v1, 0xfffffc00, v1
	v_sub_u32_e32 v0, v0, v1
	v_readlane_b32 s6, v253, 54
	v_lshrrev_b32_e32 v1, 4, v0
	v_ashrrev_i32_e32 v3, 31, v18
	s_add_u32 s4, s0, 0x13900000
	v_readlane_b32 s7, v253, 55
	v_bitop3_b32 v0, v1, v0, 32 bitop3:0x6c
	v_lshrrev_b32_e32 v3, 26, v3
	s_addc_u32 s33, s1, 0
	s_and_b32 s98, s2, 7
	s_mul_i32 s98, s98, 0xe00000
	s_add_u32 s4, s4, s98
	s_addc_u32 s33, s33, 0
	s_lshl_b64 s[6:7], s[6:7], 21
	v_ashrrev_i32_e32 v1, 31, v0
	v_add_u32_e32 v3, v18, v3
	s_add_u32 s6, s0, s6
	v_lshrrev_b32_e32 v1, 26, v1
	v_ashrrev_i32_e32 v3, 6, v3
	s_addc_u32 s7, s1, s7
	v_add_u32_e32 v1, v0, v1
	v_lshlrev_b32_e32 v4, 3, v3
	s_add_u32 s34, s6, 0x8340000
	v_ashrrev_i32_e32 v2, 6, v1
	v_and_b32_e32 v4, -16, v4
	s_addc_u32 s35, s7, 0
	s_ashr_i32 s17, s16, 31
	v_add_u32_e32 v4, v2, v4
	v_and_b32_e32 v2, 3, v2
	s_lshl_b64 s[8:9], s[16:17], 9
	v_and_or_b32 v2, v4, s14, v2
	v_readlane_b32 s14, v254, 53
	s_mul_i32 s14, s8, s14
	s_mul_hi_u32 s15, s8, s95
	s_add_i32 s18, s15, s14
	s_lshr_b64 s[14:15], s[16:17], 23
	v_readlane_b32 s22, v254, 50
	s_mul_i32 s15, s14, s95
	v_readlane_b32 s23, v254, 51
	v_and_b32_e32 v1, 0xc0, v1
	s_add_i32 s18, s18, s15
	s_mul_i32 s15, s8, s23
	s_mul_hi_u32 s21, s8, s22
	s_ashr_i32 s20, s10, 6
	v_lshrrev_b32_e32 v5, 2, v4
	v_lshlrev_b32_e32 v6, 1, v4
	v_sub_u32_e32 v0, v0, v1
	s_add_i32 s15, s21, s15
	s_mul_i32 s14, s14, s22
	s_ashr_i32 s11, s10, 8
	s_lshl_b64 s[6:7], s[16:17], 8
	s_lshl_b32 s36, s20, 10
	v_and_b32_e32 v5, 4, v5
	v_and_b32_e32 v6, 24, v6
	v_lshlrev_b32_e32 v3, 5, v3
	v_ashrrev_i16_sdwa v0, v205, sext(v0) dst_sel:DWORD dst_unused:UNUSED_PAD src0_sel:DWORD src1_sel:BYTE_0
	s_add_i32 s15, s15, s14
	s_mul_i32 s14, s8, s22
	v_or3_b32 v2, v2, v5, v6
	v_and_b32_e32 v15, 32, v3
	v_bfe_i32 v16, v0, 0, 16
	s_add_u32 s30, s34, s14
	v_mul_lo_u32 v2, v2, s16
	v_add_u32_e32 v0, v15, v16
	s_addc_u32 s31, s35, s15
	s_add_i32 s37, s36, 0
	v_add_lshl_u32 v180, v2, v0, 1
	s_add_i32 m0, s37, 0x10000
	s_mul_i32 s19, s8, s95
	global_load_lds_dwordx4 v180, s[30:31]
	s_add_i32 m0, s37, 0x12000
	s_add_u32 s14, s30, s6
	global_load_lds_dwordx4 v156, s[30:31]
	s_addc_u32 s15, s31, s7
	s_add_i32 m0, s37, 0x14000
	v_mul_lo_u32 v17, v4, s16
	global_load_lds_dwordx4 v180, s[14:15]
	s_add_i32 m0, s37, 0x16000
	s_add_u32 s28, s4, s19
	v_mov_b32_e32 v157, v181
	s_addc_u32 s29, s33, s18
	s_add_i32 s38, s37, 0x2000
	s_waitcnt vmcnt(0)
	v_add_lshl_u32 v160, v0, v17, 1
	v_lshl_add_u64 v[4:5], s[14:15], 0, v[180:181]
	v_lshl_add_u64 v[6:7], s[14:15], 0, v[156:157]
	global_load_lds_dwordx4 v156, s[14:15]
	s_mov_b32 m0, s37
	s_add_u32 s14, s28, s6
	global_load_lds_dwordx4 v160, s[28:29]
	s_mov_b32 m0, s38
	s_addc_u32 s15, s29, s7
	s_add_i32 s39, s37, 0x4000
	global_load_lds_dwordx4 v158, s[28:29]
	s_mov_b32 m0, s39
	s_add_i32 s46, s37, 0x6000
	global_load_lds_dwordx4 v160, s[14:15]
	s_mov_b32 m0, s46
	v_mov_b32_e32 v161, v181
	global_load_lds_dwordx4 v158, s[14:15]
	v_mov_b32_e32 v159, v181
	s_cmp_eq_u32 s11, 1
	v_mov_b32_e32 v240, 1
	v_lshl_add_u64 v[0:1], s[30:31], 0, v[180:181]
	v_lshl_add_u64 v[2:3], s[30:31], 0, v[156:157]
	v_lshl_add_u64 v[8:9], s[28:29], 0, v[160:161]
	v_lshl_add_u64 v[10:11], s[28:29], 0, v[158:159]
	s_cselect_b64 s[14:15], -1, 0
	s_cmp_lg_u32 s11, 1
	s_cbranch_scc1 .LBB0_1038
	s_barrier

.Lxl_9:
	s_mov_b64 s[6:7], exec
	v_mbcnt_lo_u32_b32 v0, s6, 0
	v_mbcnt_hi_u32_b32 v0, s7, v0
	v_cmp_eq_u32_e32 vcc, 0, v0
	s_waitcnt vmcnt(0)
	buffer_inv sc1
	s_and_saveexec_b64 s[8:9], vcc
	s_cbranch_execz .LBB0_550
	s_bcnt1_i32_b64 s4, s[6:7]
	v_readlane_b32 s6, v254, 28
	v_mov_b32_e32 v0, s4
	v_readlane_b32 s7, v254, 29
	s_nop 4
	global_atomic_add v181, v0, s[6:7]
	s_branch .LBB0_550
.LBB0_1299:
	v_readlane_b32 s4, v253, 32
	v_readlane_b32 s10, v253, 38
	v_readlane_b32 s11, v253, 39
	v_readlane_b32 s12, v253, 40
	v_readlane_b32 s13, v253, 41
	v_readlane_b32 s14, v253, 42
	v_readlane_b32 s15, v253, 43
	v_readlane_b32 s16, v253, 44
	v_readlane_b32 s17, v253, 45
	v_readlane_b32 s18, v253, 46
	v_readlane_b32 s19, v253, 47
	s_mov_b64 s[10:11], s[14:15]
	s_mov_b64 s[12:13], s[16:17]
	s_mov_b64 s[14:15], s[18:19]
	s_mov_b32 s0, 0x8000
	v_lshrrev_b32_e32 v0, 6, v218
	s_and_b32 s98, s2, 7
	s_lshl_b32 s98, s98, 12
	s_lshr_b32 s99, s2, 3
	s_lshl_b32 s99, s99, 7
	s_or_b32 s98, s98, s99
	v_lshl_add_u32 v16, v0, 4, s98
	v_cmp_gt_i32_e32 vcc, s0, v16
	v_readlane_b32 s5, v253, 33
	v_readlane_b32 s6, v253, 34
	v_readlane_b32 s7, v253, 35
	v_readlane_b32 s8, v253, 36
	v_readlane_b32 s9, v253, 37
	s_and_saveexec_b64 s[0:1], vcc
	s_cbranch_execz .LBB0_1302
	v_lshlrev_b32_e32 v0, 5, v218
	v_and_b32_e32 v17, 0x7e0, v0
	global_load_dwordx4 v[0:3], v17, s[10:11] offset:16
	global_load_dwordx4 v[4:7], v17, s[10:11]
	global_load_dwordx4 v[8:11], v17, s[10:11] offset:2064
	global_load_dwordx4 v[12:15], v17, s[10:11] offset:2048
	v_ashrrev_i32_e32 v17, 31, v16
	v_lshlrev_b64 v[18:19], 12, v[16:17]
	v_and_b32_e32 v22, 63, v218
	s_mov_b32 s0, 2
	v_lshl_or_b32 v18, v22, 5, v18
	v_lshl_add_u64 v[18:19], s[12:13], 0, v[18:19]
	s_mov_b64 s[2:3], 0x1000
	s_ashr_i32 s1, s0, 31
	v_lshlrev_b64 v[20:21], 11, v[16:17]
	v_lshl_add_u64 v[18:19], v[18:19], 0, s[2:3]
	s_lshl_b64 s[2:3], s[0:1], 12
	v_lshl_or_b32 v20, v22, 4, v20
	s_lshl_b64 s[4:5], s[0:1], 11
	v_lshlrev_b64 v[22:23], 6, v[16:17]
	s_lshl_b64 s[6:7], s[0:1], 6
	s_mov_b64 s[8:9], 0
	v_mov_b32_e32 v17, 0x358637bd
	s_mov_b32 s1, 0xc00000
	v_readfirstlane_b32 s10, v16
	s_nop 3
	s_add_i32 s10, s10, 15
